# adds pipelined P6 and P9 residual epilogues (all base loads in flight, counted vmcnt) on top of rsq/DPP/barrier-shift edits
# speedup vs baseline: 1.0185x; 1.0020x over previous
; #define PG8_STAGE(bufoff, gbase, voff) do { _Pragma("unroll") for (int _i = 0; _i < 2; ++_i) \
;         __builtin_amdgcn_global_load_lds((const unsigned*)((const char*)(gbase) + (voff)[_i]), (PG8_LAS unsigned*)(lds + (bufoff) + ldsw + _i * 8192), 16, 0, 0); } while (0)
; #define PG8_LDA(dst, b, h) do { _Pragma("unroll") for (int m = 0; m < 4; ++m) _Pragma("unroll") for (int k = 0; k < 2; ++k) dst[m][k] = *(const PG8_LAS bf16x8*)(lds + PG8_SA(b, h) + aoff + m * 2048 + k * 1024); } while (0)
; #define PG8_LDB(dst, b, h) do { _Pragma("unroll") for (int n = 0; n < 2; ++n) _Pragma("unroll") for (int k = 0; k < 2; ++k) dst[n][k] = *(const PG8_LAS bf16x8*)(lds + PG8_SB(b, h) + boff + n * 2048 + k * 1024); } while (0)
; #define PG8_MMA(ai, bj, At, Bt) do { __builtin_amdgcn_s_setprio(1); _Pragma("unroll") for (int m = 0; m < 4; ++m) _Pragma("unroll") for (int n = 0; n < 2; ++n) _Pragma("unroll") for (int k = 0; k < 2; ++k) \
;         acc[ai][bj][m][n] = __builtin_amdgcn_mfma_f32_16x16x32_bf16(Bt[n][k], At[m][k], acc[ai][bj][m][n], 0, 0, 0); __builtin_amdgcn_s_setprio(0); } while (0)
; template <class Epi, class Sched, bool ALIGN_EPI = false, bool SP2 = false>
; __device__ __forceinline__ void gemm_phase(PG8_LAS unsigned char* lds, const Gemm g, const Sched& S, const Epi& E, int wave_in) {
;     ...
;             if constexpr (SP2) {
;             PG8_LDB(B0, 0, 0); PG8_LDB(B1, 0, 1); PG8_SCHED; PG8_LDA(At, 0, 0); PG8_STAGE(PG8_SA(1, 1), a1 + hstep, voffA);
;             PG8_WAIT_V(8); PG8_WAIT_L(0); PG8_BAR; PG8_MMA(0, 0, At, B0); PG8_MMA(0, 1, At, B1); PG8_BAR; PG8_SCHED;
;             PG8_LDA(At, 0, 1); PG8_STAGE(PG8_SB(0, 0), b2, voffB); PG8_STAGE(PG8_SB(0, 1), b2 + hstep, voffB); PG8_STAGE(PG8_SA(0, 0), a2, voffA);
;             PG8_WAIT_V(8); PG8_WAIT_L(0); PG8_BAR; PG8_MMA(1, 0, At, B0); PG8_MMA(1, 1, At, B1); PG8_BAR; PG8_SCHED;
;             PG8_LDB(B0, 1, 0); PG8_LDB(B1, 1, 1); PG8_SCHED; PG8_LDA(At, 1, 0); PG8_STAGE(PG8_SA(0, 1), a2 + hstep, voffA);
;             PG8_WAIT_V(8); PG8_WAIT_L(0); PG8_BAR; PG8_MMA(0, 0, At, B0); PG8_MMA(0, 1, At, B1); PG8_BAR; PG8_SCHED;
;             PG8_LDA(At, 1, 1); PG8_STAGE(PG8_SB(1, 0), b3, voffB); PG8_STAGE(PG8_SB(1, 1), b3 + hstep, voffB); PG8_STAGE(PG8_SA(1, 0), a3, voffA);
;             PG8_WAIT_V(8); PG8_WAIT_L(0); PG8_BAR; PG8_MMA(1, 0, At, B0); PG8_MMA(1, 1, At, B1); PG8_BAR; PG8_SCHED;
.LBB0_845:
	ds_read_b128 v[140:143], v147
	ds_read_b128 v[152:155], v147 offset:1024
	ds_read_b128 v[156:159], v147 offset:2048
	ds_read_b128 v[160:163], v147 offset:3072
	ds_read_b128 v[164:167], v148
	ds_read_b128 v[168:171], v148 offset:1024
	ds_read_b128 v[172:175], v148 offset:2048
	ds_read_b128 v[176:179], v148 offset:3072
	s_add_u32 s26, s24, 0xfff80080
	s_addc_u32 s27, s25, -1
	s_cmp_eq_u32 s48, 28
	s_cselect_b32 s29, s15, s27
	s_cselect_b32 s28, s21, s26
	s_cselect_b32 s27, s13, s47
	s_cselect_b32 s26, s45, s46
	v_lshl_add_u64 v[212:213], s[24:25], 0, v[132:133]
	s_add_i32 m0, s23, 0xc000
	ds_read_b128 v[180:183], v149
	ds_read_b128 v[184:187], v149 offset:1024
	ds_read_b128 v[188:191], v149 offset:2048
	ds_read_b128 v[192:195], v149 offset:3072
	ds_read_b128 v[196:199], v149 offset:4096
	ds_read_b128 v[200:203], v149 offset:5120
	ds_read_b128 v[204:207], v149 offset:6144
	ds_read_b128 v[208:211], v149 offset:7168
	global_load_lds_dwordx4 v[212:213], off
	v_lshl_add_u64 v[212:213], s[24:25], 0, v[134:135]
	s_add_i32 m0, s23, 0xe000
	s_nop 0
	global_load_lds_dwordx4 v[212:213], off
	s_waitcnt vmcnt(8)
	s_waitcnt lgkmcnt(0)
	s_barrier
	s_setprio 1
	s_waitcnt lgkmcnt(0)
	v_mfma_f32_16x16x32_bf16 v[124:127], v[140:143], v[180:183], v[124:127]
	v_mfma_f32_16x16x32_bf16 v[120:123], v[156:159], v[180:183], v[120:123]
	v_mfma_f32_16x16x32_bf16 v[108:111], v[140:143], v[188:191], v[108:111]
	v_mfma_f32_16x16x32_bf16 v[104:107], v[156:159], v[188:191], v[104:107]
	v_mfma_f32_16x16x32_bf16 v[92:95], v[140:143], v[196:199], v[92:95]
	v_mfma_f32_16x16x32_bf16 v[88:91], v[156:159], v[196:199], v[88:91]
	v_mfma_f32_16x16x32_bf16 v[76:79], v[140:143], v[204:207], v[76:79]
	v_mfma_f32_16x16x32_bf16 v[72:75], v[156:159], v[204:207], v[72:75]
	v_mfma_f32_16x16x32_bf16 v[124:127], v[152:155], v[184:187], v[124:127]
	v_mfma_f32_16x16x32_bf16 v[120:123], v[160:163], v[184:187], v[120:123]
	v_mfma_f32_16x16x32_bf16 v[108:111], v[152:155], v[192:195], v[108:111]
	v_mfma_f32_16x16x32_bf16 v[104:107], v[160:163], v[192:195], v[104:107]
	v_mfma_f32_16x16x32_bf16 v[92:95], v[152:155], v[200:203], v[92:95]
	v_mfma_f32_16x16x32_bf16 v[88:91], v[160:163], v[200:203], v[88:91]
	v_mfma_f32_16x16x32_bf16 v[76:79], v[152:155], v[208:211], v[76:79]
	v_mfma_f32_16x16x32_bf16 v[72:75], v[160:163], v[208:211], v[72:75]
	s_setprio 0
	s_setprio 1
	v_mfma_f32_16x16x32_bf16 v[116:119], v[164:167], v[180:183], v[116:119]
	v_mfma_f32_16x16x32_bf16 v[112:115], v[172:175], v[180:183], v[112:115]
	v_mfma_f32_16x16x32_bf16 v[100:103], v[164:167], v[188:191], v[100:103]
	v_mfma_f32_16x16x32_bf16 v[96:99], v[172:175], v[188:191], v[96:99]
	v_mfma_f32_16x16x32_bf16 v[84:87], v[164:167], v[196:199], v[84:87]
	v_mfma_f32_16x16x32_bf16 v[80:83], v[172:175], v[196:199], v[80:83]
	v_mfma_f32_16x16x32_bf16 v[68:71], v[164:167], v[204:207], v[68:71]
	v_mfma_f32_16x16x32_bf16 v[64:67], v[172:175], v[204:207], v[64:67]
	v_mfma_f32_16x16x32_bf16 v[116:119], v[168:171], v[184:187], v[116:119]
	v_mfma_f32_16x16x32_bf16 v[112:115], v[176:179], v[184:187], v[112:115]
	v_mfma_f32_16x16x32_bf16 v[100:103], v[168:171], v[192:195], v[100:103]
	v_mfma_f32_16x16x32_bf16 v[96:99], v[176:179], v[192:195], v[96:99]
	s_barrier
	s_setprio 3
	v_mfma_f32_16x16x32_bf16 v[84:87], v[168:171], v[200:203], v[84:87]
	v_mfma_f32_16x16x32_bf16 v[80:83], v[176:179], v[200:203], v[80:83]
	v_mfma_f32_16x16x32_bf16 v[68:71], v[168:171], v[208:211], v[68:71]
	v_mfma_f32_16x16x32_bf16 v[64:67], v[176:179], v[208:211], v[64:67]
	s_setprio 0
	s_add_i32 s49, s43, s30
	v_lshl_add_u64 v[212:213], s[26:27], 0, v[128:129]
	s_mov_b32 m0, s49
	ds_read_b128 v[180:183], v149 offset:16384
	ds_read_b128 v[184:187], v149 offset:17408
	ds_read_b128 v[188:191], v149 offset:18432
	ds_read_b128 v[192:195], v149 offset:19456
	ds_read_b128 v[196:199], v149 offset:20480
	ds_read_b128 v[200:203], v149 offset:21504
	ds_read_b128 v[204:207], v149 offset:22528
	ds_read_b128 v[208:211], v149 offset:23552
	global_load_lds_dwordx4 v[212:213], off
	s_add_i32 m0, s49, 0x2000
	s_add_u32 s50, s26, 0x80000
	v_lshl_add_u64 v[214:215], s[26:27], 0, v[130:131]
	s_addc_u32 s51, s27, 0
	s_add_i32 s49, s44, s30
	global_load_lds_dwordx4 v[214:215], off
	v_lshl_add_u64 v[216:217], s[50:51], 0, v[128:129]
	s_mov_b32 m0, s49
	v_lshl_add_u64 v[218:219], s[28:29], 0, v[130:131]
	global_load_lds_dwordx4 v[216:217], off
	v_lshl_add_u64 v[216:217], s[50:51], 0, v[130:131]
	s_add_i32 m0, s49, 0x2000
	s_nop 0
	global_load_lds_dwordx4 v[216:217], off
	v_lshl_add_u64 v[216:217], s[28:29], 0, v[128:129]
	s_mov_b32 m0, s23
	s_nop 0
	global_load_lds_dwordx4 v[216:217], off
	s_mov_b32 m0, s34
	s_nop 0
	global_load_lds_dwordx4 v[218:219], off
	s_waitcnt vmcnt(8)
	s_waitcnt lgkmcnt(0)
	s_barrier
; #define PG8_STAGE(bufoff, gbase, voff) do { _Pragma("unroll") for (int _i = 0; _i < 2; ++_i) \
;         __builtin_amdgcn_global_load_lds((const unsigned*)((const char*)(gbase) + (voff)[_i]), (PG8_LAS unsigned*)(lds + (bufoff) + ldsw + _i * 8192), 16, 0, 0); } while (0)
; #define PG8_LDA(dst, b, h) do { _Pragma("unroll") for (int m = 0; m < 4; ++m) _Pragma("unroll") for (int k = 0; k < 2; ++k) dst[m][k] = *(const PG8_LAS bf16x8*)(lds + PG8_SA(b, h) + aoff + m * 2048 + k * 1024); } while (0)
; #define PG8_LDB(dst, b, h) do { _Pragma("unroll") for (int n = 0; n < 2; ++n) _Pragma("unroll") for (int k = 0; k < 2; ++k) dst[n][k] = *(const PG8_LAS bf16x8*)(lds + PG8_SB(b, h) + boff + n * 2048 + k * 1024); } while (0)
; #define PG8_MMA(ai, bj, At, Bt) do { __builtin_amdgcn_s_setprio(1); _Pragma("unroll") for (int m = 0; m < 4; ++m) _Pragma("unroll") for (int n = 0; n < 2; ++n) _Pragma("unroll") for (int k = 0; k < 2; ++k) \
;         acc[ai][bj][m][n] = __builtin_amdgcn_mfma_f32_16x16x32_bf16(Bt[n][k], At[m][k], acc[ai][bj][m][n], 0, 0, 0); __builtin_amdgcn_s_setprio(0); } while (0)
; template <class Epi, class Sched, bool ALIGN_EPI = false, bool SP2 = false>
; __device__ __forceinline__ void gemm_phase(PG8_LAS unsigned char* lds, const Gemm g, const Sched& S, const Epi& E, int wave_in) {
;     ...
;             if constexpr (SP2) {
;             PG8_LDB(B0, 0, 0); PG8_LDB(B1, 0, 1); PG8_SCHED; PG8_LDA(At, 0, 0); PG8_STAGE(PG8_SA(1, 1), a1 + hstep, voffA);
;             PG8_WAIT_V(8); PG8_WAIT_L(0); PG8_BAR; PG8_MMA(0, 0, At, B0); PG8_MMA(0, 1, At, B1); PG8_BAR; PG8_SCHED;
;             PG8_LDA(At, 0, 1); PG8_STAGE(PG8_SB(0, 0), b2, voffB); PG8_STAGE(PG8_SB(0, 1), b2 + hstep, voffB); PG8_STAGE(PG8_SA(0, 0), a2, voffA);
;             PG8_WAIT_V(8); PG8_WAIT_L(0); PG8_BAR; PG8_MMA(1, 0, At, B0); PG8_MMA(1, 1, At, B1); PG8_BAR; PG8_SCHED;
;             PG8_LDB(B0, 1, 0); PG8_LDB(B1, 1, 1); PG8_SCHED; PG8_LDA(At, 1, 0); PG8_STAGE(PG8_SA(0, 1), a2 + hstep, voffA);
;             PG8_WAIT_V(8); PG8_WAIT_L(0); PG8_BAR; PG8_MMA(0, 0, At, B0); PG8_MMA(0, 1, At, B1); PG8_BAR; PG8_SCHED;
;             PG8_LDA(At, 1, 1); PG8_STAGE(PG8_SB(1, 0), b3, voffB); PG8_STAGE(PG8_SB(1, 1), b3 + hstep, voffB); PG8_STAGE(PG8_SA(1, 0), a3, voffA);
;             PG8_WAIT_V(8); PG8_WAIT_L(0); PG8_BAR; PG8_MMA(1, 0, At, B0); PG8_MMA(1, 1, At, B1); PG8_BAR; PG8_SCHED;
	s_setprio 1
	s_waitcnt lgkmcnt(0)
	v_mfma_f32_16x16x32_bf16 v[60:63], v[140:143], v[180:183], v[60:63]
	v_mfma_f32_16x16x32_bf16 v[56:59], v[156:159], v[180:183], v[56:59]
	v_mfma_f32_16x16x32_bf16 v[44:47], v[140:143], v[188:191], v[44:47]
	v_mfma_f32_16x16x32_bf16 v[40:43], v[156:159], v[188:191], v[40:43]
	v_mfma_f32_16x16x32_bf16 v[28:31], v[140:143], v[196:199], v[28:31]
	v_mfma_f32_16x16x32_bf16 v[24:27], v[156:159], v[196:199], v[24:27]
	v_mfma_f32_16x16x32_bf16 v[12:15], v[140:143], v[204:207], v[12:15]
	v_mfma_f32_16x16x32_bf16 v[8:11], v[156:159], v[204:207], v[8:11]
	v_mfma_f32_16x16x32_bf16 v[60:63], v[152:155], v[184:187], v[60:63]
	v_mfma_f32_16x16x32_bf16 v[56:59], v[160:163], v[184:187], v[56:59]
	v_mfma_f32_16x16x32_bf16 v[44:47], v[152:155], v[192:195], v[44:47]
	v_mfma_f32_16x16x32_bf16 v[40:43], v[160:163], v[192:195], v[40:43]
	v_mfma_f32_16x16x32_bf16 v[28:31], v[152:155], v[200:203], v[28:31]
	v_mfma_f32_16x16x32_bf16 v[24:27], v[160:163], v[200:203], v[24:27]
	v_mfma_f32_16x16x32_bf16 v[12:15], v[152:155], v[208:211], v[12:15]
	v_mfma_f32_16x16x32_bf16 v[8:11], v[160:163], v[208:211], v[8:11]
	s_setprio 0
	s_setprio 1
	v_mfma_f32_16x16x32_bf16 v[52:55], v[164:167], v[180:183], v[52:55]
	v_mfma_f32_16x16x32_bf16 v[48:51], v[172:175], v[180:183], v[48:51]
	v_mfma_f32_16x16x32_bf16 v[36:39], v[164:167], v[188:191], v[36:39]
	v_mfma_f32_16x16x32_bf16 v[32:35], v[172:175], v[188:191], v[32:35]
	v_mfma_f32_16x16x32_bf16 v[20:23], v[164:167], v[196:199], v[20:23]
	v_mfma_f32_16x16x32_bf16 v[16:19], v[172:175], v[196:199], v[16:19]
	v_mfma_f32_16x16x32_bf16 v[4:7], v[164:167], v[204:207], v[4:7]
	v_mfma_f32_16x16x32_bf16 v[0:3], v[172:175], v[204:207], v[0:3]
	v_mfma_f32_16x16x32_bf16 v[52:55], v[168:171], v[184:187], v[52:55]
	v_mfma_f32_16x16x32_bf16 v[48:51], v[176:179], v[184:187], v[48:51]
	v_mfma_f32_16x16x32_bf16 v[36:39], v[168:171], v[192:195], v[36:39]
	v_mfma_f32_16x16x32_bf16 v[32:35], v[176:179], v[192:195], v[32:35]
	s_barrier
	s_setprio 3
	v_mfma_f32_16x16x32_bf16 v[20:23], v[168:171], v[200:203], v[20:23]
	v_mfma_f32_16x16x32_bf16 v[16:19], v[176:179], v[200:203], v[16:19]
	v_mfma_f32_16x16x32_bf16 v[4:7], v[168:171], v[208:211], v[4:7]
	v_mfma_f32_16x16x32_bf16 v[0:3], v[176:179], v[208:211], v[0:3]
	s_setprio 0
	s_add_i32 s49, 0, 0x18000
	v_add_u32_e32 v151, s49, v145
	s_add_i32 s50, 0, 0x1c000
	ds_read_b128 v[140:143], v151
	ds_read_b128 v[152:155], v151 offset:1024
	ds_read_b128 v[156:159], v151 offset:2048
	ds_read_b128 v[160:163], v151 offset:3072
	v_add_u32_e32 v151, s50, v145
	ds_read_b128 v[164:167], v151
	ds_read_b128 v[168:171], v151 offset:1024
	ds_read_b128 v[172:175], v151 offset:2048
	ds_read_b128 v[176:179], v151 offset:3072
	s_add_u32 s28, s28, 0x80000
	s_addc_u32 s29, s29, 0
	s_mov_b32 m0, s35
	v_lshl_add_u64 v[220:221], s[28:29], 0, v[128:129]
	ds_read_b128 v[180:183], v149 offset:32768
	ds_read_b128 v[184:187], v149 offset:33792
	ds_read_b128 v[188:191], v149 offset:34816
	ds_read_b128 v[192:195], v149 offset:35840
	ds_read_b128 v[196:199], v149 offset:36864
	ds_read_b128 v[200:203], v149 offset:37888
	ds_read_b128 v[204:207], v149 offset:38912
	ds_read_b128 v[208:211], v149 offset:39936
	global_load_lds_dwordx4 v[220:221], off
	v_lshl_add_u64 v[220:221], s[28:29], 0, v[130:131]
	s_mov_b32 m0, s36
	s_nop 0
	global_load_lds_dwordx4 v[220:221], off
	s_waitcnt vmcnt(8)
	s_waitcnt lgkmcnt(0)
	s_barrier
	s_setprio 1
	s_waitcnt lgkmcnt(0)
	v_mfma_f32_16x16x32_bf16 v[124:127], v[140:143], v[180:183], v[124:127]
	v_mfma_f32_16x16x32_bf16 v[120:123], v[156:159], v[180:183], v[120:123]
	v_mfma_f32_16x16x32_bf16 v[108:111], v[140:143], v[188:191], v[108:111]
	v_mfma_f32_16x16x32_bf16 v[104:107], v[156:159], v[188:191], v[104:107]
	v_mfma_f32_16x16x32_bf16 v[92:95], v[140:143], v[196:199], v[92:95]
	v_mfma_f32_16x16x32_bf16 v[88:91], v[156:159], v[196:199], v[88:91]
	v_mfma_f32_16x16x32_bf16 v[76:79], v[140:143], v[204:207], v[76:79]
	v_mfma_f32_16x16x32_bf16 v[72:75], v[156:159], v[204:207], v[72:75]
	v_mfma_f32_16x16x32_bf16 v[124:127], v[152:155], v[184:187], v[124:127]
	v_mfma_f32_16x16x32_bf16 v[120:123], v[160:163], v[184:187], v[120:123]
	v_mfma_f32_16x16x32_bf16 v[108:111], v[152:155], v[192:195], v[108:111]
	v_mfma_f32_16x16x32_bf16 v[104:107], v[160:163], v[192:195], v[104:107]
	v_mfma_f32_16x16x32_bf16 v[92:95], v[152:155], v[200:203], v[92:95]
	v_mfma_f32_16x16x32_bf16 v[88:91], v[160:163], v[200:203], v[88:91]
	v_mfma_f32_16x16x32_bf16 v[76:79], v[152:155], v[208:211], v[76:79]
	v_mfma_f32_16x16x32_bf16 v[72:75], v[160:163], v[208:211], v[72:75]
	s_setprio 0
	s_setprio 1
	v_mfma_f32_16x16x32_bf16 v[116:119], v[164:167], v[180:183], v[116:119]
	v_mfma_f32_16x16x32_bf16 v[112:115], v[172:175], v[180:183], v[112:115]
	v_mfma_f32_16x16x32_bf16 v[100:103], v[164:167], v[188:191], v[100:103]
	v_mfma_f32_16x16x32_bf16 v[96:99], v[172:175], v[188:191], v[96:99]
	v_mfma_f32_16x16x32_bf16 v[84:87], v[164:167], v[196:199], v[84:87]
	v_mfma_f32_16x16x32_bf16 v[80:83], v[172:175], v[196:199], v[80:83]
	v_mfma_f32_16x16x32_bf16 v[68:71], v[164:167], v[204:207], v[68:71]
	v_mfma_f32_16x16x32_bf16 v[64:67], v[172:175], v[204:207], v[64:67]
	v_mfma_f32_16x16x32_bf16 v[116:119], v[168:171], v[184:187], v[116:119]
	v_mfma_f32_16x16x32_bf16 v[112:115], v[176:179], v[184:187], v[112:115]
	v_mfma_f32_16x16x32_bf16 v[100:103], v[168:171], v[192:195], v[100:103]
	v_mfma_f32_16x16x32_bf16 v[96:99], v[176:179], v[192:195], v[96:99]
	s_barrier
; #define PG8_WAIT_V(n) asm volatile("s_waitcnt vmcnt(" #n ")" ::: "memory")
; #define PG8_WAIT_L(n) asm volatile("s_waitcnt lgkmcnt(" #n ")" ::: "memory")
; #define PG8_BAR __builtin_amdgcn_s_barrier()
;     __device__ __forceinline__ void operator()(const f32x4 (&acc)[2][2][4][2], const Unit& u, int wr, int wc, int fr, int fq) const {
;     ...
;             for (int m = 0; m < 4; ++m) { const int row = u.pm * BM + ai * HALF + wr * 64 + m * 16 + fr; const size_t off = (size_t)row * ldc + col0;
;                 float ss = 0.f;
; #pragma unroll
;                 for (int bj = 0; bj < 2; ++bj)
; #pragma unroll
;                     for (int n = 0; n < 2; ++n) { f32x4 bs;
;                         if (BASE_BF16) { const u32x2 t = *(const u32x2*)((const bf16_t*)base + off + bj * HALF + n * 16);
;                             bs = (f32x4){__builtin_bit_cast(float, t.x << 16), __builtin_bit_cast(float, t.x & 0xffff0000u), __builtin_bit_cast(float, t.y << 16), __builtin_bit_cast(float, t.y & 0xffff0000u)}; }
;                         else bs = *(const f32x4*)((const float*)base + off + bj * HALF + n * 16);
; template <class Epi, class Sched, bool ALIGN_EPI = false, bool SP2 = false>
; __device__ __forceinline__ void gemm_phase(PG8_LAS unsigned char* lds, const Gemm g, const Sched& S, const Epi& E, int wave_in) {
;     ...
;             if constexpr (SP2) {
;             PG8_LDB(B0, 0, 0); PG8_LDB(B1, 0, 1); PG8_SCHED; PG8_LDA(At, 0, 0); PG8_STAGE(PG8_SA(1, 1), a1 + hstep, voffA);
;             PG8_WAIT_V(8); PG8_WAIT_L(0); PG8_BAR; PG8_MMA(0, 0, At, B0); PG8_MMA(0, 1, At, B1); PG8_BAR; PG8_SCHED;
;             PG8_LDA(At, 0, 1); PG8_STAGE(PG8_SB(0, 0), b2, voffB); PG8_STAGE(PG8_SB(0, 1), b2 + hstep, voffB); PG8_STAGE(PG8_SA(0, 0), a2, voffA);
;             PG8_WAIT_V(8); PG8_WAIT_L(0); PG8_BAR; PG8_MMA(1, 0, At, B0); PG8_MMA(1, 1, At, B1); PG8_BAR; PG8_SCHED;
;             PG8_LDB(B0, 1, 0); PG8_LDB(B1, 1, 1); PG8_SCHED; PG8_LDA(At, 1, 0); PG8_STAGE(PG8_SA(0, 1), a2 + hstep, voffA);
;             PG8_WAIT_V(8); PG8_WAIT_L(0); PG8_BAR; PG8_MMA(0, 0, At, B0); PG8_MMA(0, 1, At, B1); PG8_BAR; PG8_SCHED;
;             PG8_LDA(At, 1, 1); PG8_STAGE(PG8_SB(1, 0), b3, voffB); PG8_STAGE(PG8_SB(1, 1), b3 + hstep, voffB); PG8_STAGE(PG8_SA(1, 0), a3, voffA);
;             PG8_WAIT_V(8); PG8_WAIT_L(0); PG8_BAR; PG8_MMA(1, 0, At, B0); PG8_MMA(1, 1, At, B1); PG8_BAR; PG8_SCHED;
	s_setprio 3
	v_mfma_f32_16x16x32_bf16 v[84:87], v[168:171], v[200:203], v[84:87]
	v_mfma_f32_16x16x32_bf16 v[80:83], v[176:179], v[200:203], v[80:83]
	v_mfma_f32_16x16x32_bf16 v[68:71], v[168:171], v[208:211], v[68:71]
	v_mfma_f32_16x16x32_bf16 v[64:67], v[176:179], v[208:211], v[64:67]
	s_setprio 0
	s_add_i32 s28, s49, s30
	v_lshl_add_u64 v[212:213], v[212:213], 0, s[2:3]
	s_mov_b32 m0, s28
	ds_read_b128 v[180:183], v149 offset:49152
	ds_read_b128 v[184:187], v149 offset:50176
	ds_read_b128 v[188:191], v149 offset:51200
	ds_read_b128 v[192:195], v149 offset:52224
	ds_read_b128 v[196:199], v149 offset:53248
	ds_read_b128 v[200:203], v149 offset:54272
	ds_read_b128 v[204:207], v149 offset:55296
	ds_read_b128 v[208:211], v149 offset:56320
	global_load_lds_dwordx4 v[212:213], off
	s_add_i32 m0, s28, 0x2000
	s_add_u32 s26, s26, 0x80080
	v_lshl_add_u64 v[212:213], v[214:215], 0, s[2:3]
	s_addc_u32 s27, s27, 0
	s_add_i32 s28, s50, s30
	global_load_lds_dwordx4 v[212:213], off
	v_lshl_add_u64 v[212:213], s[26:27], 0, v[128:129]
	s_mov_b32 m0, s28
	s_nop 0
	global_load_lds_dwordx4 v[212:213], off
	v_lshl_add_u64 v[212:213], s[26:27], 0, v[130:131]
	s_add_i32 m0, s28, 0x2000
	s_nop 0
	global_load_lds_dwordx4 v[212:213], off
	v_lshl_add_u64 v[212:213], v[216:217], 0, s[2:3]
	s_mov_b32 m0, s38
	s_nop 0
	global_load_lds_dwordx4 v[212:213], off
	v_lshl_add_u64 v[212:213], v[218:219], 0, s[2:3]
	s_mov_b32 m0, s39
	s_nop 0
	global_load_lds_dwordx4 v[212:213], off
	s_waitcnt vmcnt(8)
	s_waitcnt lgkmcnt(0)
	s_barrier
	s_setprio 1
	s_waitcnt lgkmcnt(0)
	v_mfma_f32_16x16x32_bf16 v[60:63], v[140:143], v[180:183], v[60:63]
	v_mfma_f32_16x16x32_bf16 v[56:59], v[156:159], v[180:183], v[56:59]
	v_mfma_f32_16x16x32_bf16 v[44:47], v[140:143], v[188:191], v[44:47]
	v_mfma_f32_16x16x32_bf16 v[40:43], v[156:159], v[188:191], v[40:43]
	v_mfma_f32_16x16x32_bf16 v[28:31], v[140:143], v[196:199], v[28:31]
	v_mfma_f32_16x16x32_bf16 v[24:27], v[156:159], v[196:199], v[24:27]
	v_mfma_f32_16x16x32_bf16 v[12:15], v[140:143], v[204:207], v[12:15]
	v_mfma_f32_16x16x32_bf16 v[8:11], v[156:159], v[204:207], v[8:11]
	v_mfma_f32_16x16x32_bf16 v[60:63], v[152:155], v[184:187], v[60:63]
	v_mfma_f32_16x16x32_bf16 v[56:59], v[160:163], v[184:187], v[56:59]
	v_mfma_f32_16x16x32_bf16 v[44:47], v[152:155], v[192:195], v[44:47]
	v_mfma_f32_16x16x32_bf16 v[40:43], v[160:163], v[192:195], v[40:43]
	v_mfma_f32_16x16x32_bf16 v[28:31], v[152:155], v[200:203], v[28:31]
	v_mfma_f32_16x16x32_bf16 v[24:27], v[160:163], v[200:203], v[24:27]
	v_mfma_f32_16x16x32_bf16 v[12:15], v[152:155], v[208:211], v[12:15]
	v_mfma_f32_16x16x32_bf16 v[8:11], v[160:163], v[208:211], v[8:11]
	s_setprio 0
	s_setprio 1
	v_mfma_f32_16x16x32_bf16 v[52:55], v[164:167], v[180:183], v[52:55]
	v_mfma_f32_16x16x32_bf16 v[48:51], v[172:175], v[180:183], v[48:51]
	v_mfma_f32_16x16x32_bf16 v[36:39], v[164:167], v[188:191], v[36:39]
	v_mfma_f32_16x16x32_bf16 v[32:35], v[172:175], v[188:191], v[32:35]
	v_mfma_f32_16x16x32_bf16 v[20:23], v[164:167], v[196:199], v[20:23]
	v_mfma_f32_16x16x32_bf16 v[16:19], v[172:175], v[196:199], v[16:19]
	v_mfma_f32_16x16x32_bf16 v[4:7], v[164:167], v[204:207], v[4:7]
	v_mfma_f32_16x16x32_bf16 v[0:3], v[172:175], v[204:207], v[0:3]
	v_mfma_f32_16x16x32_bf16 v[52:55], v[168:171], v[184:187], v[52:55]
	v_mfma_f32_16x16x32_bf16 v[48:51], v[176:179], v[184:187], v[48:51]
	v_mfma_f32_16x16x32_bf16 v[36:39], v[168:171], v[192:195], v[36:39]
	v_mfma_f32_16x16x32_bf16 v[32:35], v[176:179], v[192:195], v[32:35]
	s_barrier
	s_setprio 3
	v_mfma_f32_16x16x32_bf16 v[20:23], v[168:171], v[200:203], v[20:23]
	v_mfma_f32_16x16x32_bf16 v[16:19], v[176:179], v[200:203], v[16:19]
	v_mfma_f32_16x16x32_bf16 v[4:7], v[168:171], v[208:211], v[4:7]
	v_mfma_f32_16x16x32_bf16 v[0:3], v[176:179], v[208:211], v[0:3]
	s_setprio 0
	s_add_i32 s48, s48, 2
	s_add_u32 s24, s24, 0x100
	s_addc_u32 s25, s25, 0
	s_add_u32 s46, s46, 0x100
	s_addc_u32 s47, s47, 0
	s_cmp_gt_u32 s48, 29
	s_cbranch_scc0 .LBB0_845
	v_lshl_add_u32 v142, s20, 8, v144
	v_lshl_or_b32 v140, s22, 8, v146
	v_lshlrev_b32_e32 v143, 12, v142
	v_lshl_add_u32 v143, v140, 1, v143
	v_lshlrev_b32_e32 v142, 2, v142
	v_xor_b32_e32 v151, 16, v150
	v_xor_b32_e32 v141, 32, v150
	v_lshlrev_b32_e32 v151, 2, v151
	v_lshlrev_b32_e32 v141, 2, v141
	v_mov_b32_e32 v140, v143
	global_load_dwordx2 v[152:153], v140, s[76:77]
	global_load_dwordx2 v[154:155], v140, s[76:77] offset:32
	global_load_dwordx2 v[156:157], v140, s[76:77] offset:256
	global_load_dwordx2 v[158:159], v140, s[76:77] offset:288
	v_add_u32_e32 v140, 0x10000, v143
	global_load_dwordx2 v[160:161], v140, s[76:77]
	global_load_dwordx2 v[162:163], v140, s[76:77] offset:32
	global_load_dwordx2 v[164:165], v140, s[76:77] offset:256
	global_load_dwordx2 v[166:167], v140, s[76:77] offset:288
	v_add_u32_e32 v140, 0x20000, v143
	global_load_dwordx2 v[168:169], v140, s[76:77]
	global_load_dwordx2 v[170:171], v140, s[76:77] offset:32
	global_load_dwordx2 v[172:173], v140, s[76:77] offset:256
	global_load_dwordx2 v[174:175], v140, s[76:77] offset:288
	v_add_u32_e32 v140, 0x30000, v143
	global_load_dwordx2 v[176:177], v140, s[76:77]
	global_load_dwordx2 v[178:179], v140, s[76:77] offset:32
	global_load_dwordx2 v[180:181], v140, s[76:77] offset:256
	global_load_dwordx2 v[182:183], v140, s[76:77] offset:288
	v_add_u32_e32 v140, 0x80000, v143
	global_load_dwordx2 v[184:185], v140, s[76:77]
	global_load_dwordx2 v[186:187], v140, s[76:77] offset:32
	global_load_dwordx2 v[188:189], v140, s[76:77] offset:256
	global_load_dwordx2 v[190:191], v140, s[76:77] offset:288
	v_add_u32_e32 v140, 0x90000, v143
	global_load_dwordx2 v[192:193], v140, s[76:77]
	global_load_dwordx2 v[194:195], v140, s[76:77] offset:32
	global_load_dwordx2 v[196:197], v140, s[76:77] offset:256
	global_load_dwordx2 v[198:199], v140, s[76:77] offset:288
	v_add_u32_e32 v140, 0xa0000, v143
	global_load_dwordx2 v[200:201], v140, s[76:77]
	global_load_dwordx2 v[202:203], v140, s[76:77] offset:32
	global_load_dwordx2 v[204:205], v140, s[76:77] offset:256
	global_load_dwordx2 v[206:207], v140, s[76:77] offset:288
	s_and_b64 vcc, exec, s[4:5]
	s_cbranch_vccz .LBB0_848
	s_barrier
; __device__ __forceinline__ unsigned cvt_pk_bf16(float lo, float hi) { unsigned r; asm volatile("v_cvt_pk_bf16_f32 %0, %1, %2" : "=v"(r) : "v"(lo), "v"(hi)); return r; }
;     __device__ __forceinline__ void operator()(const f32x4 (&acc)[2][2][4][2], const Unit& u, int wr, int wc, int fr, int fq) const {
;     ...
;             for (int m = 0; m < 4; ++m) { const int row = u.pm * BM + ai * HALF + wr * 64 + m * 16 + fr; const size_t off = (size_t)row * ldc + col0;
;                 float ss = 0.f;
; #pragma unroll
;                 for (int bj = 0; bj < 2; ++bj)
; #pragma unroll
;                     for (int n = 0; n < 2; ++n) { f32x4 bs;
;                         if (BASE_BF16) { const u32x2 t = *(const u32x2*)((const bf16_t*)base + off + bj * HALF + n * 16);
;                             bs = (f32x4){__builtin_bit_cast(float, t.x << 16), __builtin_bit_cast(float, t.x & 0xffff0000u), __builtin_bit_cast(float, t.y << 16), __builtin_bit_cast(float, t.y & 0xffff0000u)}; }
;                         else bs = *(const f32x4*)((const float*)base + off + bj * HALF + n * 16);
;                         const f32x4 v = bs + acc[ai][bj][m][n] * scale;
;                         u32x2 w; w.x = cvt_pk_bf16(v[0], v[1]); w.y = cvt_pk_bf16(v[2], v[3]);
;                         *(u32x2*)(xn + off + bj * HALF + n * 16) = w;
;                         ss += (v[0] * v[0] + v[1] * v[1]) + (v[2] * v[2] + v[3] * v[3]); }
.LBB0_848:
	s_waitcnt vmcnt(24)
	v_mov_b32_e32 v140, v143
	v_lshlrev_b32_e32 v216, 16, v152
	v_and_b32_e32 v217, 0xffff0000, v152
	v_lshlrev_b32_e32 v218, 16, v153
	v_and_b32_e32 v219, 0xffff0000, v153
	v_pk_add_f32 v[124:125], v[124:125], v[216:217]
	v_pk_add_f32 v[126:127], v[126:127], v[218:219]
	v_cvt_pk_bf16_f32 v152, v124, v125
	v_cvt_pk_bf16_f32 v153, v126, v127
	global_store_dwordx2 v140, v[152:153], s[68:69]
	v_mul_f32_e32 v220, v125, v125
	v_mul_f32_e32 v221, v127, v127
	v_fmac_f32_e32 v220, v124, v124
	v_fmac_f32_e32 v221, v126, v126
	v_add_f32_e32 v208, v220, v221
	v_lshlrev_b32_e32 v216, 16, v154
	v_and_b32_e32 v217, 0xffff0000, v154
	v_lshlrev_b32_e32 v218, 16, v155
	v_and_b32_e32 v219, 0xffff0000, v155
	v_pk_add_f32 v[120:121], v[120:121], v[216:217]
	v_pk_add_f32 v[122:123], v[122:123], v[218:219]
	v_cvt_pk_bf16_f32 v154, v120, v121
	v_cvt_pk_bf16_f32 v155, v122, v123
	global_store_dwordx2 v140, v[154:155], s[68:69] offset:32
	v_mul_f32_e32 v220, v121, v121
	v_mul_f32_e32 v221, v123, v123
	v_fmac_f32_e32 v220, v120, v120
	v_fmac_f32_e32 v221, v122, v122
	v_add_f32_e32 v220, v220, v221
	v_add_f32_e32 v208, v208, v220
	v_lshlrev_b32_e32 v216, 16, v156
	v_and_b32_e32 v217, 0xffff0000, v156
	v_lshlrev_b32_e32 v218, 16, v157
	v_and_b32_e32 v219, 0xffff0000, v157
	v_pk_add_f32 v[116:117], v[116:117], v[216:217]
	v_pk_add_f32 v[118:119], v[118:119], v[218:219]
	v_cvt_pk_bf16_f32 v156, v116, v117
	v_cvt_pk_bf16_f32 v157, v118, v119
	global_store_dwordx2 v140, v[156:157], s[68:69] offset:256
	v_mul_f32_e32 v220, v117, v117
	v_mul_f32_e32 v221, v119, v119
	v_fmac_f32_e32 v220, v116, v116
	v_fmac_f32_e32 v221, v118, v118
	v_add_f32_e32 v220, v220, v221
	v_add_f32_e32 v208, v208, v220
	v_lshlrev_b32_e32 v216, 16, v158
	v_and_b32_e32 v217, 0xffff0000, v158
	v_lshlrev_b32_e32 v218, 16, v159
	v_and_b32_e32 v219, 0xffff0000, v159
	v_pk_add_f32 v[112:113], v[112:113], v[216:217]
	v_pk_add_f32 v[114:115], v[114:115], v[218:219]
	v_cvt_pk_bf16_f32 v158, v112, v113
	v_cvt_pk_bf16_f32 v159, v114, v115
	global_store_dwordx2 v140, v[158:159], s[68:69] offset:288
	v_mul_f32_e32 v220, v113, v113
	v_mul_f32_e32 v221, v115, v115
	v_fmac_f32_e32 v220, v112, v112
	v_fmac_f32_e32 v221, v114, v114
	v_add_f32_e32 v220, v220, v221
	v_add_f32_e32 v208, v208, v220
	v_add_u32_e32 v140, 0xb0000, v143
	global_load_dwordx2 v[152:153], v140, s[76:77]
	global_load_dwordx2 v[154:155], v140, s[76:77] offset:32
	global_load_dwordx2 v[156:157], v140, s[76:77] offset:256
	global_load_dwordx2 v[158:159], v140, s[76:77] offset:288
	s_waitcnt vmcnt(28)
	v_add_u32_e32 v140, 0x10000, v143
	v_lshlrev_b32_e32 v216, 16, v160
	v_and_b32_e32 v217, 0xffff0000, v160
	v_lshlrev_b32_e32 v218, 16, v161
	v_and_b32_e32 v219, 0xffff0000, v161
	v_pk_add_f32 v[108:109], v[108:109], v[216:217]
	v_pk_add_f32 v[110:111], v[110:111], v[218:219]
	v_cvt_pk_bf16_f32 v160, v108, v109
	v_cvt_pk_bf16_f32 v161, v110, v111
	global_store_dwordx2 v140, v[160:161], s[68:69]
	v_mul_f32_e32 v220, v109, v109
	v_mul_f32_e32 v221, v111, v111
	v_fmac_f32_e32 v220, v108, v108
	v_fmac_f32_e32 v221, v110, v110
	v_add_f32_e32 v209, v220, v221
	v_lshlrev_b32_e32 v216, 16, v162
	v_and_b32_e32 v217, 0xffff0000, v162
	v_lshlrev_b32_e32 v218, 16, v163
	v_and_b32_e32 v219, 0xffff0000, v163
	v_pk_add_f32 v[104:105], v[104:105], v[216:217]
	v_pk_add_f32 v[106:107], v[106:107], v[218:219]
	v_cvt_pk_bf16_f32 v162, v104, v105
	v_cvt_pk_bf16_f32 v163, v106, v107
	global_store_dwordx2 v140, v[162:163], s[68:69] offset:32
	v_mul_f32_e32 v220, v105, v105
	v_mul_f32_e32 v221, v107, v107
	v_fmac_f32_e32 v220, v104, v104
	v_fmac_f32_e32 v221, v106, v106
	v_add_f32_e32 v220, v220, v221
	v_add_f32_e32 v209, v209, v220
	v_lshlrev_b32_e32 v216, 16, v164
	v_and_b32_e32 v217, 0xffff0000, v164
	v_lshlrev_b32_e32 v218, 16, v165
	v_and_b32_e32 v219, 0xffff0000, v165
	v_pk_add_f32 v[100:101], v[100:101], v[216:217]
	v_pk_add_f32 v[102:103], v[102:103], v[218:219]
	v_cvt_pk_bf16_f32 v164, v100, v101
	v_cvt_pk_bf16_f32 v165, v102, v103
	global_store_dwordx2 v140, v[164:165], s[68:69] offset:256
	v_mul_f32_e32 v220, v101, v101
	v_mul_f32_e32 v221, v103, v103
	v_fmac_f32_e32 v220, v100, v100
	v_fmac_f32_e32 v221, v102, v102
	v_add_f32_e32 v220, v220, v221
	v_add_f32_e32 v209, v209, v220
	v_lshlrev_b32_e32 v216, 16, v166
	v_and_b32_e32 v217, 0xffff0000, v166
	v_lshlrev_b32_e32 v218, 16, v167
	v_and_b32_e32 v219, 0xffff0000, v167
	v_pk_add_f32 v[96:97], v[96:97], v[216:217]
	v_pk_add_f32 v[98:99], v[98:99], v[218:219]
	v_cvt_pk_bf16_f32 v166, v96, v97
	v_cvt_pk_bf16_f32 v167, v98, v99
	global_store_dwordx2 v140, v[166:167], s[68:69] offset:288
	v_mul_f32_e32 v220, v97, v97
	v_mul_f32_e32 v221, v99, v99
	v_fmac_f32_e32 v220, v96, v96
	v_fmac_f32_e32 v221, v98, v98
	v_add_f32_e32 v220, v220, v221
	v_add_f32_e32 v209, v209, v220
	s_waitcnt vmcnt(28)
; __device__ __forceinline__ unsigned cvt_pk_bf16(float lo, float hi) { unsigned r; asm volatile("v_cvt_pk_bf16_f32 %0, %1, %2" : "=v"(r) : "v"(lo), "v"(hi)); return r; }
;     __device__ __forceinline__ void operator()(const f32x4 (&acc)[2][2][4][2], const Unit& u, int wr, int wc, int fr, int fq) const {
;     ...
;             for (int m = 0; m < 4; ++m) { const int row = u.pm * BM + ai * HALF + wr * 64 + m * 16 + fr; const size_t off = (size_t)row * ldc + col0;
;                 float ss = 0.f;
; #pragma unroll
;                 for (int bj = 0; bj < 2; ++bj)
; #pragma unroll
;                     for (int n = 0; n < 2; ++n) { f32x4 bs;
;                         if (BASE_BF16) { const u32x2 t = *(const u32x2*)((const bf16_t*)base + off + bj * HALF + n * 16);
;                             bs = (f32x4){__builtin_bit_cast(float, t.x << 16), __builtin_bit_cast(float, t.x & 0xffff0000u), __builtin_bit_cast(float, t.y << 16), __builtin_bit_cast(float, t.y & 0xffff0000u)}; }
;                         else bs = *(const f32x4*)((const float*)base + off + bj * HALF + n * 16);
;                         const f32x4 v = bs + acc[ai][bj][m][n] * scale;
;                         u32x2 w; w.x = cvt_pk_bf16(v[0], v[1]); w.y = cvt_pk_bf16(v[2], v[3]);
;                         *(u32x2*)(xn + off + bj * HALF + n * 16) = w;
;                         ss += (v[0] * v[0] + v[1] * v[1]) + (v[2] * v[2] + v[3] * v[3]); }
	v_add_u32_e32 v140, 0x20000, v143
	v_lshlrev_b32_e32 v216, 16, v168
	v_and_b32_e32 v217, 0xffff0000, v168
	v_lshlrev_b32_e32 v218, 16, v169
	v_and_b32_e32 v219, 0xffff0000, v169
	v_pk_add_f32 v[92:93], v[92:93], v[216:217]
	v_pk_add_f32 v[94:95], v[94:95], v[218:219]
	v_cvt_pk_bf16_f32 v168, v92, v93
	v_cvt_pk_bf16_f32 v169, v94, v95
	global_store_dwordx2 v140, v[168:169], s[68:69]
	v_mul_f32_e32 v220, v93, v93
	v_mul_f32_e32 v221, v95, v95
	v_fmac_f32_e32 v220, v92, v92
	v_fmac_f32_e32 v221, v94, v94
	v_add_f32_e32 v210, v220, v221
	v_lshlrev_b32_e32 v216, 16, v170
	v_and_b32_e32 v217, 0xffff0000, v170
	v_lshlrev_b32_e32 v218, 16, v171
	v_and_b32_e32 v219, 0xffff0000, v171
	v_pk_add_f32 v[88:89], v[88:89], v[216:217]
	v_pk_add_f32 v[90:91], v[90:91], v[218:219]
	v_cvt_pk_bf16_f32 v170, v88, v89
	v_cvt_pk_bf16_f32 v171, v90, v91
	global_store_dwordx2 v140, v[170:171], s[68:69] offset:32
	v_mul_f32_e32 v220, v89, v89
	v_mul_f32_e32 v221, v91, v91
	v_fmac_f32_e32 v220, v88, v88
	v_fmac_f32_e32 v221, v90, v90
	v_add_f32_e32 v220, v220, v221
	v_add_f32_e32 v210, v210, v220
	v_lshlrev_b32_e32 v216, 16, v172
	v_and_b32_e32 v217, 0xffff0000, v172
	v_lshlrev_b32_e32 v218, 16, v173
	v_and_b32_e32 v219, 0xffff0000, v173
	v_pk_add_f32 v[84:85], v[84:85], v[216:217]
	v_pk_add_f32 v[86:87], v[86:87], v[218:219]
	v_cvt_pk_bf16_f32 v172, v84, v85
	v_cvt_pk_bf16_f32 v173, v86, v87
	global_store_dwordx2 v140, v[172:173], s[68:69] offset:256
	v_mul_f32_e32 v220, v85, v85
	v_mul_f32_e32 v221, v87, v87
	v_fmac_f32_e32 v220, v84, v84
	v_fmac_f32_e32 v221, v86, v86
	v_add_f32_e32 v220, v220, v221
	v_add_f32_e32 v210, v210, v220
	v_lshlrev_b32_e32 v216, 16, v174
	v_and_b32_e32 v217, 0xffff0000, v174
	v_lshlrev_b32_e32 v218, 16, v175
	v_and_b32_e32 v219, 0xffff0000, v175
	v_pk_add_f32 v[80:81], v[80:81], v[216:217]
	v_pk_add_f32 v[82:83], v[82:83], v[218:219]
	v_cvt_pk_bf16_f32 v174, v80, v81
	v_cvt_pk_bf16_f32 v175, v82, v83
	global_store_dwordx2 v140, v[174:175], s[68:69] offset:288
	v_mul_f32_e32 v220, v81, v81
	v_mul_f32_e32 v221, v83, v83
	v_fmac_f32_e32 v220, v80, v80
	v_fmac_f32_e32 v221, v82, v82
	v_add_f32_e32 v220, v220, v221
	v_add_f32_e32 v210, v210, v220
	s_waitcnt vmcnt(28)
	v_add_u32_e32 v140, 0x30000, v143
	v_lshlrev_b32_e32 v216, 16, v176
	v_and_b32_e32 v217, 0xffff0000, v176
	v_lshlrev_b32_e32 v218, 16, v177
	v_and_b32_e32 v219, 0xffff0000, v177
	v_pk_add_f32 v[76:77], v[76:77], v[216:217]
	v_pk_add_f32 v[78:79], v[78:79], v[218:219]
	v_cvt_pk_bf16_f32 v176, v76, v77
	v_cvt_pk_bf16_f32 v177, v78, v79
	global_store_dwordx2 v140, v[176:177], s[68:69]
	v_mul_f32_e32 v220, v77, v77
	v_mul_f32_e32 v221, v79, v79
	v_fmac_f32_e32 v220, v76, v76
	v_fmac_f32_e32 v221, v78, v78
	v_add_f32_e32 v211, v220, v221
	v_lshlrev_b32_e32 v216, 16, v178
	v_and_b32_e32 v217, 0xffff0000, v178
	v_lshlrev_b32_e32 v218, 16, v179
	v_and_b32_e32 v219, 0xffff0000, v179
	v_pk_add_f32 v[72:73], v[72:73], v[216:217]
	v_pk_add_f32 v[74:75], v[74:75], v[218:219]
	v_cvt_pk_bf16_f32 v178, v72, v73
	v_cvt_pk_bf16_f32 v179, v74, v75
	global_store_dwordx2 v140, v[178:179], s[68:69] offset:32
	v_mul_f32_e32 v220, v73, v73
	v_mul_f32_e32 v221, v75, v75
	v_fmac_f32_e32 v220, v72, v72
	v_fmac_f32_e32 v221, v74, v74
	v_add_f32_e32 v220, v220, v221
	v_add_f32_e32 v211, v211, v220
	v_lshlrev_b32_e32 v216, 16, v180
	v_and_b32_e32 v217, 0xffff0000, v180
	v_lshlrev_b32_e32 v218, 16, v181
	v_and_b32_e32 v219, 0xffff0000, v181
	v_pk_add_f32 v[68:69], v[68:69], v[216:217]
	v_pk_add_f32 v[70:71], v[70:71], v[218:219]
	v_cvt_pk_bf16_f32 v180, v68, v69
	v_cvt_pk_bf16_f32 v181, v70, v71
	global_store_dwordx2 v140, v[180:181], s[68:69] offset:256
	v_mul_f32_e32 v220, v69, v69
	v_mul_f32_e32 v221, v71, v71
	v_fmac_f32_e32 v220, v68, v68
	v_fmac_f32_e32 v221, v70, v70
	v_add_f32_e32 v220, v220, v221
	v_add_f32_e32 v211, v211, v220
	v_lshlrev_b32_e32 v216, 16, v182
	v_and_b32_e32 v217, 0xffff0000, v182
	v_lshlrev_b32_e32 v218, 16, v183
	v_and_b32_e32 v219, 0xffff0000, v183
	v_pk_add_f32 v[64:65], v[64:65], v[216:217]
	v_pk_add_f32 v[66:67], v[66:67], v[218:219]
	v_cvt_pk_bf16_f32 v182, v64, v65
	v_cvt_pk_bf16_f32 v183, v66, v67
	global_store_dwordx2 v140, v[182:183], s[68:69] offset:288
	v_mul_f32_e32 v220, v65, v65
	v_mul_f32_e32 v221, v67, v67
	v_fmac_f32_e32 v220, v64, v64
	v_fmac_f32_e32 v221, v66, v66
	v_add_f32_e32 v220, v220, v221
	v_add_f32_e32 v211, v211, v220
	s_waitcnt vmcnt(28)
	v_add_u32_e32 v140, 0x80000, v143
	v_lshlrev_b32_e32 v216, 16, v184
	v_and_b32_e32 v217, 0xffff0000, v184
	v_lshlrev_b32_e32 v218, 16, v185
	v_and_b32_e32 v219, 0xffff0000, v185
	v_pk_add_f32 v[60:61], v[60:61], v[216:217]
	v_pk_add_f32 v[62:63], v[62:63], v[218:219]
	v_cvt_pk_bf16_f32 v184, v60, v61
	v_cvt_pk_bf16_f32 v185, v62, v63
	global_store_dwordx2 v140, v[184:185], s[68:69]
	v_mul_f32_e32 v220, v61, v61
	v_mul_f32_e32 v221, v63, v63
	v_fmac_f32_e32 v220, v60, v60
	v_fmac_f32_e32 v221, v62, v62
	v_add_f32_e32 v212, v220, v221
	v_lshlrev_b32_e32 v216, 16, v186
	v_and_b32_e32 v217, 0xffff0000, v186
	v_lshlrev_b32_e32 v218, 16, v187
	v_and_b32_e32 v219, 0xffff0000, v187
	v_pk_add_f32 v[56:57], v[56:57], v[216:217]
	v_pk_add_f32 v[58:59], v[58:59], v[218:219]
	v_cvt_pk_bf16_f32 v186, v56, v57
	v_cvt_pk_bf16_f32 v187, v58, v59
	global_store_dwordx2 v140, v[186:187], s[68:69] offset:32
	v_mul_f32_e32 v220, v57, v57
	v_mul_f32_e32 v221, v59, v59
	v_fmac_f32_e32 v220, v56, v56
	v_fmac_f32_e32 v221, v58, v58
	v_add_f32_e32 v220, v220, v221
	v_add_f32_e32 v212, v212, v220
	v_lshlrev_b32_e32 v216, 16, v188
	v_and_b32_e32 v217, 0xffff0000, v188
	v_lshlrev_b32_e32 v218, 16, v189
	v_and_b32_e32 v219, 0xffff0000, v189
	v_pk_add_f32 v[52:53], v[52:53], v[216:217]
	v_pk_add_f32 v[54:55], v[54:55], v[218:219]
	v_cvt_pk_bf16_f32 v188, v52, v53
	v_cvt_pk_bf16_f32 v189, v54, v55
	global_store_dwordx2 v140, v[188:189], s[68:69] offset:256
	v_mul_f32_e32 v220, v53, v53
	v_mul_f32_e32 v221, v55, v55
	v_fmac_f32_e32 v220, v52, v52
	v_fmac_f32_e32 v221, v54, v54
	v_add_f32_e32 v220, v220, v221
	v_add_f32_e32 v212, v212, v220
	v_lshlrev_b32_e32 v216, 16, v190
	v_and_b32_e32 v217, 0xffff0000, v190
	v_lshlrev_b32_e32 v218, 16, v191
	v_and_b32_e32 v219, 0xffff0000, v191
	v_pk_add_f32 v[48:49], v[48:49], v[216:217]
	v_pk_add_f32 v[50:51], v[50:51], v[218:219]
	v_cvt_pk_bf16_f32 v190, v48, v49
	v_cvt_pk_bf16_f32 v191, v50, v51
	global_store_dwordx2 v140, v[190:191], s[68:69] offset:288
	v_mul_f32_e32 v220, v49, v49
	v_mul_f32_e32 v221, v51, v51
	v_fmac_f32_e32 v220, v48, v48
	v_fmac_f32_e32 v221, v50, v50
	v_add_f32_e32 v220, v220, v221
	v_add_f32_e32 v212, v212, v220
	s_waitcnt vmcnt(28)
; __device__ __forceinline__ unsigned cvt_pk_bf16(float lo, float hi) { unsigned r; asm volatile("v_cvt_pk_bf16_f32 %0, %1, %2" : "=v"(r) : "v"(lo), "v"(hi)); return r; }
;     __device__ __forceinline__ void operator()(const f32x4 (&acc)[2][2][4][2], const Unit& u, int wr, int wc, int fr, int fq) const {
;     ...
;             for (int m = 0; m < 4; ++m) { const int row = u.pm * BM + ai * HALF + wr * 64 + m * 16 + fr; const size_t off = (size_t)row * ldc + col0;
;                 float ss = 0.f;
; #pragma unroll
;                 for (int bj = 0; bj < 2; ++bj)
; #pragma unroll
;                     for (int n = 0; n < 2; ++n) { f32x4 bs;
;                         if (BASE_BF16) { const u32x2 t = *(const u32x2*)((const bf16_t*)base + off + bj * HALF + n * 16);
;                             bs = (f32x4){__builtin_bit_cast(float, t.x << 16), __builtin_bit_cast(float, t.x & 0xffff0000u), __builtin_bit_cast(float, t.y << 16), __builtin_bit_cast(float, t.y & 0xffff0000u)}; }
;                         else bs = *(const f32x4*)((const float*)base + off + bj * HALF + n * 16);
;                         const f32x4 v = bs + acc[ai][bj][m][n] * scale;
;                         u32x2 w; w.x = cvt_pk_bf16(v[0], v[1]); w.y = cvt_pk_bf16(v[2], v[3]);
;                         *(u32x2*)(xn + off + bj * HALF + n * 16) = w;
;                         ss += (v[0] * v[0] + v[1] * v[1]) + (v[2] * v[2] + v[3] * v[3]); }
	v_add_u32_e32 v140, 0x90000, v143
	v_lshlrev_b32_e32 v216, 16, v192
	v_and_b32_e32 v217, 0xffff0000, v192
	v_lshlrev_b32_e32 v218, 16, v193
	v_and_b32_e32 v219, 0xffff0000, v193
	v_pk_add_f32 v[44:45], v[44:45], v[216:217]
	v_pk_add_f32 v[46:47], v[46:47], v[218:219]
	v_cvt_pk_bf16_f32 v192, v44, v45
	v_cvt_pk_bf16_f32 v193, v46, v47
	global_store_dwordx2 v140, v[192:193], s[68:69]
	v_mul_f32_e32 v220, v45, v45
	v_mul_f32_e32 v221, v47, v47
	v_fmac_f32_e32 v220, v44, v44
	v_fmac_f32_e32 v221, v46, v46
	v_add_f32_e32 v213, v220, v221
	v_lshlrev_b32_e32 v216, 16, v194
	v_and_b32_e32 v217, 0xffff0000, v194
	v_lshlrev_b32_e32 v218, 16, v195
	v_and_b32_e32 v219, 0xffff0000, v195
	v_pk_add_f32 v[40:41], v[40:41], v[216:217]
	v_pk_add_f32 v[42:43], v[42:43], v[218:219]
	v_cvt_pk_bf16_f32 v194, v40, v41
	v_cvt_pk_bf16_f32 v195, v42, v43
	global_store_dwordx2 v140, v[194:195], s[68:69] offset:32
	v_mul_f32_e32 v220, v41, v41
	v_mul_f32_e32 v221, v43, v43
	v_fmac_f32_e32 v220, v40, v40
	v_fmac_f32_e32 v221, v42, v42
	v_add_f32_e32 v220, v220, v221
	v_add_f32_e32 v213, v213, v220
	v_lshlrev_b32_e32 v216, 16, v196
	v_and_b32_e32 v217, 0xffff0000, v196
	v_lshlrev_b32_e32 v218, 16, v197
	v_and_b32_e32 v219, 0xffff0000, v197
	v_pk_add_f32 v[36:37], v[36:37], v[216:217]
	v_pk_add_f32 v[38:39], v[38:39], v[218:219]
	v_cvt_pk_bf16_f32 v196, v36, v37
	v_cvt_pk_bf16_f32 v197, v38, v39
	global_store_dwordx2 v140, v[196:197], s[68:69] offset:256
	v_mul_f32_e32 v220, v37, v37
	v_mul_f32_e32 v221, v39, v39
	v_fmac_f32_e32 v220, v36, v36
	v_fmac_f32_e32 v221, v38, v38
	v_add_f32_e32 v220, v220, v221
	v_add_f32_e32 v213, v213, v220
	v_lshlrev_b32_e32 v216, 16, v198
	v_and_b32_e32 v217, 0xffff0000, v198
	v_lshlrev_b32_e32 v218, 16, v199
	v_and_b32_e32 v219, 0xffff0000, v199
	v_pk_add_f32 v[32:33], v[32:33], v[216:217]
	v_pk_add_f32 v[34:35], v[34:35], v[218:219]
	v_cvt_pk_bf16_f32 v198, v32, v33
	v_cvt_pk_bf16_f32 v199, v34, v35
	global_store_dwordx2 v140, v[198:199], s[68:69] offset:288
	v_mul_f32_e32 v220, v33, v33
	v_mul_f32_e32 v221, v35, v35
	v_fmac_f32_e32 v220, v32, v32
	v_fmac_f32_e32 v221, v34, v34
	v_add_f32_e32 v220, v220, v221
	v_add_f32_e32 v213, v213, v220
	s_waitcnt vmcnt(28)
	v_add_u32_e32 v140, 0xa0000, v143
	v_lshlrev_b32_e32 v216, 16, v200
	v_and_b32_e32 v217, 0xffff0000, v200
	v_lshlrev_b32_e32 v218, 16, v201
	v_and_b32_e32 v219, 0xffff0000, v201
	v_pk_add_f32 v[28:29], v[28:29], v[216:217]
	v_pk_add_f32 v[30:31], v[30:31], v[218:219]
	v_cvt_pk_bf16_f32 v200, v28, v29
	v_cvt_pk_bf16_f32 v201, v30, v31
	global_store_dwordx2 v140, v[200:201], s[68:69]
	v_mul_f32_e32 v220, v29, v29
	v_mul_f32_e32 v221, v31, v31
	v_fmac_f32_e32 v220, v28, v28
	v_fmac_f32_e32 v221, v30, v30
	v_add_f32_e32 v214, v220, v221
	v_lshlrev_b32_e32 v216, 16, v202
	v_and_b32_e32 v217, 0xffff0000, v202
	v_lshlrev_b32_e32 v218, 16, v203
	v_and_b32_e32 v219, 0xffff0000, v203
	v_pk_add_f32 v[24:25], v[24:25], v[216:217]
	v_pk_add_f32 v[26:27], v[26:27], v[218:219]
	v_cvt_pk_bf16_f32 v202, v24, v25
	v_cvt_pk_bf16_f32 v203, v26, v27
	global_store_dwordx2 v140, v[202:203], s[68:69] offset:32
	v_mul_f32_e32 v220, v25, v25
	v_mul_f32_e32 v221, v27, v27
	v_fmac_f32_e32 v220, v24, v24
	v_fmac_f32_e32 v221, v26, v26
	v_add_f32_e32 v220, v220, v221
	v_add_f32_e32 v214, v214, v220
	v_lshlrev_b32_e32 v216, 16, v204
	v_and_b32_e32 v217, 0xffff0000, v204
	v_lshlrev_b32_e32 v218, 16, v205
	v_and_b32_e32 v219, 0xffff0000, v205
	v_pk_add_f32 v[20:21], v[20:21], v[216:217]
	v_pk_add_f32 v[22:23], v[22:23], v[218:219]
	v_cvt_pk_bf16_f32 v204, v20, v21
	v_cvt_pk_bf16_f32 v205, v22, v23
	global_store_dwordx2 v140, v[204:205], s[68:69] offset:256
	v_mul_f32_e32 v220, v21, v21
	v_mul_f32_e32 v221, v23, v23
	v_fmac_f32_e32 v220, v20, v20
	v_fmac_f32_e32 v221, v22, v22
	v_add_f32_e32 v220, v220, v221
	v_add_f32_e32 v214, v214, v220
	v_lshlrev_b32_e32 v216, 16, v206
	v_and_b32_e32 v217, 0xffff0000, v206
	v_lshlrev_b32_e32 v218, 16, v207
	v_and_b32_e32 v219, 0xffff0000, v207
	v_pk_add_f32 v[16:17], v[16:17], v[216:217]
	v_pk_add_f32 v[18:19], v[18:19], v[218:219]
	v_cvt_pk_bf16_f32 v206, v16, v17
	v_cvt_pk_bf16_f32 v207, v18, v19
	global_store_dwordx2 v140, v[206:207], s[68:69] offset:288
	v_mul_f32_e32 v220, v17, v17
	v_mul_f32_e32 v221, v19, v19
	v_fmac_f32_e32 v220, v16, v16
	v_fmac_f32_e32 v221, v18, v18
	v_add_f32_e32 v220, v220, v221
	v_add_f32_e32 v214, v214, v220
	s_waitcnt vmcnt(24)
; __device__ __forceinline__ unsigned cvt_pk_bf16(float lo, float hi) { unsigned r; asm volatile("v_cvt_pk_bf16_f32 %0, %1, %2" : "=v"(r) : "v"(lo), "v"(hi)); return r; }
;     __device__ __forceinline__ void operator()(const f32x4 (&acc)[2][2][4][2], const Unit& u, int wr, int wc, int fr, int fq) const {
;     ...
;                     for (int n = 0; n < 2; ++n) { f32x4 bs;
;                         if (BASE_BF16) { const u32x2 t = *(const u32x2*)((const bf16_t*)base + off + bj * HALF + n * 16);
;                             bs = (f32x4){__builtin_bit_cast(float, t.x << 16), __builtin_bit_cast(float, t.x & 0xffff0000u), __builtin_bit_cast(float, t.y << 16), __builtin_bit_cast(float, t.y & 0xffff0000u)}; }
;                         else bs = *(const f32x4*)((const float*)base + off + bj * HALF + n * 16);
;                         const f32x4 v = bs + acc[ai][bj][m][n] * scale;
;                         u32x2 w; w.x = cvt_pk_bf16(v[0], v[1]); w.y = cvt_pk_bf16(v[2], v[3]);
;                         *(u32x2*)(xn + off + bj * HALF + n * 16) = w;
;                         ss += (v[0] * v[0] + v[1] * v[1]) + (v[2] * v[2] + v[3] * v[3]); }
;                 ss += __shfl_xor(ss, 16); ss += __shfl_xor(ss, 32);
;                 if (fq == 0) __hip_atomic_fetch_add(rowss + row, ss, __ATOMIC_RELAXED, __HIP_MEMORY_SCOPE_AGENT); }
	v_add_u32_e32 v140, 0xb0000, v143
	v_lshlrev_b32_e32 v216, 16, v152
	v_and_b32_e32 v217, 0xffff0000, v152
	v_lshlrev_b32_e32 v218, 16, v153
	v_and_b32_e32 v219, 0xffff0000, v153
	v_pk_add_f32 v[12:13], v[12:13], v[216:217]
	v_pk_add_f32 v[14:15], v[14:15], v[218:219]
	v_cvt_pk_bf16_f32 v152, v12, v13
	v_cvt_pk_bf16_f32 v153, v14, v15
	global_store_dwordx2 v140, v[152:153], s[68:69]
	v_mul_f32_e32 v220, v13, v13
	v_mul_f32_e32 v221, v15, v15
	v_fmac_f32_e32 v220, v12, v12
	v_fmac_f32_e32 v221, v14, v14
	v_add_f32_e32 v215, v220, v221
	v_lshlrev_b32_e32 v216, 16, v154
	v_and_b32_e32 v217, 0xffff0000, v154
	v_lshlrev_b32_e32 v218, 16, v155
	v_and_b32_e32 v219, 0xffff0000, v155
	v_pk_add_f32 v[8:9], v[8:9], v[216:217]
	v_pk_add_f32 v[10:11], v[10:11], v[218:219]
	v_cvt_pk_bf16_f32 v154, v8, v9
	v_cvt_pk_bf16_f32 v155, v10, v11
	global_store_dwordx2 v140, v[154:155], s[68:69] offset:32
	v_mul_f32_e32 v220, v9, v9
	v_mul_f32_e32 v221, v11, v11
	v_fmac_f32_e32 v220, v8, v8
	v_fmac_f32_e32 v221, v10, v10
	v_add_f32_e32 v220, v220, v221
	v_add_f32_e32 v215, v215, v220
	v_lshlrev_b32_e32 v216, 16, v156
	v_and_b32_e32 v217, 0xffff0000, v156
	v_lshlrev_b32_e32 v218, 16, v157
	v_and_b32_e32 v219, 0xffff0000, v157
	v_pk_add_f32 v[4:5], v[4:5], v[216:217]
	v_pk_add_f32 v[6:7], v[6:7], v[218:219]
	v_cvt_pk_bf16_f32 v156, v4, v5
	v_cvt_pk_bf16_f32 v157, v6, v7
	global_store_dwordx2 v140, v[156:157], s[68:69] offset:256
	v_mul_f32_e32 v220, v5, v5
	v_mul_f32_e32 v221, v7, v7
	v_fmac_f32_e32 v220, v4, v4
	v_fmac_f32_e32 v221, v6, v6
	v_add_f32_e32 v220, v220, v221
	v_add_f32_e32 v215, v215, v220
	v_lshlrev_b32_e32 v216, 16, v158
	v_and_b32_e32 v217, 0xffff0000, v158
	v_lshlrev_b32_e32 v218, 16, v159
	v_and_b32_e32 v219, 0xffff0000, v159
	v_pk_add_f32 v[0:1], v[0:1], v[216:217]
	v_pk_add_f32 v[2:3], v[2:3], v[218:219]
	v_cvt_pk_bf16_f32 v158, v0, v1
	v_cvt_pk_bf16_f32 v159, v2, v3
	global_store_dwordx2 v140, v[158:159], s[68:69] offset:288
	v_mul_f32_e32 v220, v1, v1
	v_mul_f32_e32 v221, v3, v3
	v_fmac_f32_e32 v220, v0, v0
	v_fmac_f32_e32 v221, v2, v2
	v_add_f32_e32 v220, v220, v221
	v_add_f32_e32 v215, v215, v220
	ds_bpermute_b32 v160, v151, v208
	ds_bpermute_b32 v161, v151, v209
	ds_bpermute_b32 v162, v151, v210
	ds_bpermute_b32 v163, v151, v211
	ds_bpermute_b32 v164, v151, v212
	ds_bpermute_b32 v165, v151, v213
	ds_bpermute_b32 v166, v151, v214
	ds_bpermute_b32 v167, v151, v215
	s_waitcnt lgkmcnt(0)
	v_add_f32_e32 v208, v208, v160
	v_add_f32_e32 v209, v209, v161
	v_add_f32_e32 v210, v210, v162
	v_add_f32_e32 v211, v211, v163
	v_add_f32_e32 v212, v212, v164
	v_add_f32_e32 v213, v213, v165
	v_add_f32_e32 v214, v214, v166
	v_add_f32_e32 v215, v215, v167
	ds_bpermute_b32 v160, v141, v208
	ds_bpermute_b32 v161, v141, v209
	ds_bpermute_b32 v162, v141, v210
	ds_bpermute_b32 v163, v141, v211
	ds_bpermute_b32 v164, v141, v212
	ds_bpermute_b32 v165, v141, v213
	ds_bpermute_b32 v166, v141, v214
	ds_bpermute_b32 v167, v141, v215
	s_waitcnt lgkmcnt(0)
	v_add_f32_e32 v208, v208, v160
	v_add_f32_e32 v209, v209, v161
	v_add_f32_e32 v210, v210, v162
	v_add_f32_e32 v211, v211, v163
	v_add_f32_e32 v212, v212, v164
	v_add_f32_e32 v213, v213, v165
	v_add_f32_e32 v214, v214, v166
	v_add_f32_e32 v215, v215, v167
	s_and_saveexec_b64 s[20:21], s[6:7]
	v_mov_b32_e32 v140, v142
	global_atomic_add_f32 v140, v208, s[10:11]
	v_add_u32_e32 v140, 0x40, v142
	global_atomic_add_f32 v140, v209, s[10:11]
	v_add_u32_e32 v140, 0x80, v142
	global_atomic_add_f32 v140, v210, s[10:11]
	v_add_u32_e32 v140, 0xc0, v142
	global_atomic_add_f32 v140, v211, s[10:11]
	v_add_u32_e32 v140, 0x200, v142
	global_atomic_add_f32 v140, v212, s[10:11]
	v_add_u32_e32 v140, 0x240, v142
	global_atomic_add_f32 v140, v213, s[10:11]
	v_add_u32_e32 v140, 0x280, v142
	global_atomic_add_f32 v140, v214, s[10:11]
	v_add_u32_e32 v140, 0x2c0, v142
	global_atomic_add_f32 v140, v215, s[10:11]
	s_or_b64 exec, exec, s[20:21]
	s_andn2_b64 vcc, exec, s[8:9]
	s_mov_b64 s[8:9], -1
	s_cbranch_vccnz .LBB0_837
	s_andn2_b64 vcc, exec, s[0:1]
	s_cbranch_vccnz .LBB0_836
	s_barrier
	s_branch .LBB0_836

; #define PG8_STAGE(bufoff, gbase, voff) do { _Pragma("unroll") for (int _i = 0; _i < 2; ++_i) \
;         __builtin_amdgcn_global_load_lds((const unsigned*)((const char*)(gbase) + (voff)[_i]), (PG8_LAS unsigned*)(lds + (bufoff) + ldsw + _i * 8192), 16, 0, 0); } while (0)
; #define PG8_LDA(dst, b, h) do { _Pragma("unroll") for (int m = 0; m < 4; ++m) _Pragma("unroll") for (int k = 0; k < 2; ++k) dst[m][k] = *(const PG8_LAS bf16x8*)(lds + PG8_SA(b, h) + aoff + m * 2048 + k * 1024); } while (0)
; #define PG8_LDB(dst, b, h) do { _Pragma("unroll") for (int n = 0; n < 2; ++n) _Pragma("unroll") for (int k = 0; k < 2; ++k) dst[n][k] = *(const PG8_LAS bf16x8*)(lds + PG8_SB(b, h) + boff + n * 2048 + k * 1024); } while (0)
; #define PG8_MMA(ai, bj, At, Bt) do { __builtin_amdgcn_s_setprio(1); _Pragma("unroll") for (int m = 0; m < 4; ++m) _Pragma("unroll") for (int n = 0; n < 2; ++n) _Pragma("unroll") for (int k = 0; k < 2; ++k) \
;         acc[ai][bj][m][n] = __builtin_amdgcn_mfma_f32_16x16x32_bf16(Bt[n][k], At[m][k], acc[ai][bj][m][n], 0, 0, 0); __builtin_amdgcn_s_setprio(0); } while (0)
; #define PG8_BAR __builtin_amdgcn_s_barrier()
; template <class Epi, class Sched, bool ALIGN_EPI = false, bool SP2 = false>
; __device__ __forceinline__ void gemm_phase(PG8_LAS unsigned char* lds, const Gemm g, const Sched& S, const Epi& E, int wave_in) {
;     ...
;             PG8_LDB(B0, 0, 0); PG8_LDB(B1, 0, 1); PG8_SCHED; PG8_LDA(At, 0, 0); PG8_STAGE(PG8_SA(1, 1), a1 + hstep, voffA);
;             PG8_WAIT_V(8); PG8_WAIT_L(0); PG8_BAR; PG8_MMA(0, 0, At, B0); PG8_MMA(0, 1, At, B1); PG8_BAR; PG8_SCHED;
;             PG8_LDA(At, 0, 1); PG8_STAGE(PG8_SB(0, 0), b2, voffB); PG8_STAGE(PG8_SB(0, 1), b2 + hstep, voffB); PG8_STAGE(PG8_SA(0, 0), a2, voffA);
;             PG8_WAIT_V(8); PG8_WAIT_L(0); PG8_BAR; PG8_MMA(1, 0, At, B0); PG8_MMA(1, 1, At, B1); PG8_BAR; PG8_SCHED;
;             PG8_LDB(B0, 1, 0); PG8_LDB(B1, 1, 1); PG8_SCHED; PG8_LDA(At, 1, 0); PG8_STAGE(PG8_SA(0, 1), a2 + hstep, voffA);
;             PG8_WAIT_V(8); PG8_WAIT_L(0); PG8_BAR; PG8_MMA(0, 0, At, B0); PG8_MMA(0, 1, At, B1); PG8_BAR; PG8_SCHED;
;             PG8_LDA(At, 1, 1); PG8_STAGE(PG8_SB(1, 0), b3, voffB); PG8_STAGE(PG8_SB(1, 1), b3 + hstep, voffB); PG8_STAGE(PG8_SA(1, 0), a3, voffA);
;             PG8_WAIT_V(8); PG8_WAIT_L(0); PG8_BAR; PG8_MMA(1, 0, At, B0); PG8_MMA(1, 1, At, B1); PG8_BAR; PG8_SCHED;
.LBB0_1009:
	ds_read_b128 v[140:143], v147
	ds_read_b128 v[150:153], v147 offset:1024
	ds_read_b128 v[154:157], v147 offset:2048
	ds_read_b128 v[158:161], v147 offset:3072
	ds_read_b128 v[162:165], v148
	ds_read_b128 v[166:169], v148 offset:1024
	ds_read_b128 v[170:173], v148 offset:2048
	ds_read_b128 v[174:177], v148 offset:3072
	s_add_u32 s18, s16, 0x100
	s_addc_u32 s19, s17, 0
	s_cmpk_eq_i32 s45, 0x54
	s_cselect_b32 s23, s5, s19
	s_cselect_b32 s22, s4, s18
	s_cselect_b32 s21, s15, s44
	s_cselect_b32 s20, s14, s43
	v_lshl_add_u64 v[210:211], s[16:17], 0, v[132:133]
	s_add_i32 m0, s28, 0xc000
	ds_read_b128 v[178:181], v149
	ds_read_b128 v[182:185], v149 offset:1024
	ds_read_b128 v[186:189], v149 offset:2048
	ds_read_b128 v[190:193], v149 offset:3072
	ds_read_b128 v[194:197], v149 offset:4096
	ds_read_b128 v[198:201], v149 offset:5120
	ds_read_b128 v[202:205], v149 offset:6144
	ds_read_b128 v[206:209], v149 offset:7168
	global_load_lds_dwordx4 v[210:211], off
	v_lshl_add_u64 v[210:211], s[16:17], 0, v[134:135]
	s_add_i32 m0, s28, 0xe000
	s_nop 0
	global_load_lds_dwordx4 v[210:211], off
	s_waitcnt vmcnt(8)
	s_waitcnt lgkmcnt(0)
	s_barrier
	s_setprio 1
	s_waitcnt lgkmcnt(0)
	v_mfma_f32_16x16x32_bf16 v[124:127], v[140:143], v[178:181], v[124:127]
	v_mfma_f32_16x16x32_bf16 v[120:123], v[154:157], v[178:181], v[120:123]
	v_mfma_f32_16x16x32_bf16 v[112:115], v[140:143], v[186:189], v[112:115]
	v_mfma_f32_16x16x32_bf16 v[104:107], v[154:157], v[186:189], v[104:107]
	v_mfma_f32_16x16x32_bf16 v[96:99], v[140:143], v[194:197], v[96:99]
	v_mfma_f32_16x16x32_bf16 v[88:91], v[154:157], v[194:197], v[88:91]
	v_mfma_f32_16x16x32_bf16 v[80:83], v[140:143], v[202:205], v[80:83]
	v_mfma_f32_16x16x32_bf16 v[72:75], v[154:157], v[202:205], v[72:75]
	v_mfma_f32_16x16x32_bf16 v[124:127], v[150:153], v[182:185], v[124:127]
	v_mfma_f32_16x16x32_bf16 v[120:123], v[158:161], v[182:185], v[120:123]
	v_mfma_f32_16x16x32_bf16 v[112:115], v[150:153], v[190:193], v[112:115]
	v_mfma_f32_16x16x32_bf16 v[104:107], v[158:161], v[190:193], v[104:107]
	v_mfma_f32_16x16x32_bf16 v[96:99], v[150:153], v[198:201], v[96:99]
	v_mfma_f32_16x16x32_bf16 v[88:91], v[158:161], v[198:201], v[88:91]
	v_mfma_f32_16x16x32_bf16 v[80:83], v[150:153], v[206:209], v[80:83]
	v_mfma_f32_16x16x32_bf16 v[72:75], v[158:161], v[206:209], v[72:75]
	s_setprio 0
	s_setprio 1
	v_mfma_f32_16x16x32_bf16 v[116:119], v[162:165], v[178:181], v[116:119]
	v_mfma_f32_16x16x32_bf16 v[108:111], v[170:173], v[178:181], v[108:111]
	v_mfma_f32_16x16x32_bf16 v[100:103], v[162:165], v[186:189], v[100:103]
	v_mfma_f32_16x16x32_bf16 v[92:95], v[170:173], v[186:189], v[92:95]
	v_mfma_f32_16x16x32_bf16 v[84:87], v[162:165], v[194:197], v[84:87]
	v_mfma_f32_16x16x32_bf16 v[76:79], v[170:173], v[194:197], v[76:79]
	v_mfma_f32_16x16x32_bf16 v[68:71], v[162:165], v[202:205], v[68:71]
	v_mfma_f32_16x16x32_bf16 v[64:67], v[170:173], v[202:205], v[64:67]
	v_mfma_f32_16x16x32_bf16 v[116:119], v[166:169], v[182:185], v[116:119]
	v_mfma_f32_16x16x32_bf16 v[108:111], v[174:177], v[182:185], v[108:111]
	v_mfma_f32_16x16x32_bf16 v[100:103], v[166:169], v[190:193], v[100:103]
	v_mfma_f32_16x16x32_bf16 v[92:95], v[174:177], v[190:193], v[92:95]
	s_barrier
	s_setprio 3
	v_mfma_f32_16x16x32_bf16 v[84:87], v[166:169], v[198:201], v[84:87]
	v_mfma_f32_16x16x32_bf16 v[76:79], v[174:177], v[198:201], v[76:79]
	v_mfma_f32_16x16x32_bf16 v[68:71], v[166:169], v[206:209], v[68:71]
	v_mfma_f32_16x16x32_bf16 v[64:67], v[174:177], v[206:209], v[64:67]
	s_setprio 0
	s_add_i32 s16, s37, s25
	v_lshl_add_u64 v[210:211], s[20:21], 0, v[128:129]
	s_mov_b32 m0, s16
	ds_read_b128 v[178:181], v149 offset:16384
	ds_read_b128 v[182:185], v149 offset:17408
	ds_read_b128 v[186:189], v149 offset:18432
	ds_read_b128 v[190:193], v149 offset:19456
	ds_read_b128 v[194:197], v149 offset:20480
	ds_read_b128 v[198:201], v149 offset:21504
	ds_read_b128 v[202:205], v149 offset:22528
	ds_read_b128 v[206:209], v149 offset:23552
	global_load_lds_dwordx4 v[210:211], off
	s_add_i32 m0, s16, 0x2000
	s_add_u32 s16, s20, 0x160000
	v_lshl_add_u64 v[212:213], s[20:21], 0, v[130:131]
	s_addc_u32 s17, s21, 0
	s_add_i32 s46, s38, s25
	global_load_lds_dwordx4 v[212:213], off
	v_lshl_add_u64 v[214:215], s[16:17], 0, v[128:129]
	s_mov_b32 m0, s46
	v_lshl_add_u64 v[216:217], s[22:23], 0, v[130:131]
	global_load_lds_dwordx4 v[214:215], off
	v_lshl_add_u64 v[214:215], s[16:17], 0, v[130:131]
	s_add_i32 m0, s46, 0x2000
	s_nop 0
	global_load_lds_dwordx4 v[214:215], off
	v_lshl_add_u64 v[214:215], s[22:23], 0, v[128:129]
	s_mov_b32 m0, s28
	s_nop 0
	global_load_lds_dwordx4 v[214:215], off
	s_mov_b32 m0, s29
	s_nop 0
	global_load_lds_dwordx4 v[216:217], off
	s_waitcnt vmcnt(8)
	s_waitcnt lgkmcnt(0)
	s_barrier
; #define PG8_STAGE(bufoff, gbase, voff) do { _Pragma("unroll") for (int _i = 0; _i < 2; ++_i) \
;         __builtin_amdgcn_global_load_lds((const unsigned*)((const char*)(gbase) + (voff)[_i]), (PG8_LAS unsigned*)(lds + (bufoff) + ldsw + _i * 8192), 16, 0, 0); } while (0)
; #define PG8_LDA(dst, b, h) do { _Pragma("unroll") for (int m = 0; m < 4; ++m) _Pragma("unroll") for (int k = 0; k < 2; ++k) dst[m][k] = *(const PG8_LAS bf16x8*)(lds + PG8_SA(b, h) + aoff + m * 2048 + k * 1024); } while (0)
; #define PG8_LDB(dst, b, h) do { _Pragma("unroll") for (int n = 0; n < 2; ++n) _Pragma("unroll") for (int k = 0; k < 2; ++k) dst[n][k] = *(const PG8_LAS bf16x8*)(lds + PG8_SB(b, h) + boff + n * 2048 + k * 1024); } while (0)
; #define PG8_MMA(ai, bj, At, Bt) do { __builtin_amdgcn_s_setprio(1); _Pragma("unroll") for (int m = 0; m < 4; ++m) _Pragma("unroll") for (int n = 0; n < 2; ++n) _Pragma("unroll") for (int k = 0; k < 2; ++k) \
;         acc[ai][bj][m][n] = __builtin_amdgcn_mfma_f32_16x16x32_bf16(Bt[n][k], At[m][k], acc[ai][bj][m][n], 0, 0, 0); __builtin_amdgcn_s_setprio(0); } while (0)
; #define PG8_BAR __builtin_amdgcn_s_barrier()
; template <class Epi, class Sched, bool ALIGN_EPI = false, bool SP2 = false>
; __device__ __forceinline__ void gemm_phase(PG8_LAS unsigned char* lds, const Gemm g, const Sched& S, const Epi& E, int wave_in) {
;     ...
;             PG8_LDB(B0, 0, 0); PG8_LDB(B1, 0, 1); PG8_SCHED; PG8_LDA(At, 0, 0); PG8_STAGE(PG8_SA(1, 1), a1 + hstep, voffA);
;             PG8_WAIT_V(8); PG8_WAIT_L(0); PG8_BAR; PG8_MMA(0, 0, At, B0); PG8_MMA(0, 1, At, B1); PG8_BAR; PG8_SCHED;
;             PG8_LDA(At, 0, 1); PG8_STAGE(PG8_SB(0, 0), b2, voffB); PG8_STAGE(PG8_SB(0, 1), b2 + hstep, voffB); PG8_STAGE(PG8_SA(0, 0), a2, voffA);
;             PG8_WAIT_V(8); PG8_WAIT_L(0); PG8_BAR; PG8_MMA(1, 0, At, B0); PG8_MMA(1, 1, At, B1); PG8_BAR; PG8_SCHED;
;             PG8_LDB(B0, 1, 0); PG8_LDB(B1, 1, 1); PG8_SCHED; PG8_LDA(At, 1, 0); PG8_STAGE(PG8_SA(0, 1), a2 + hstep, voffA);
;             PG8_WAIT_V(8); PG8_WAIT_L(0); PG8_BAR; PG8_MMA(0, 0, At, B0); PG8_MMA(0, 1, At, B1); PG8_BAR; PG8_SCHED;
;             PG8_LDA(At, 1, 1); PG8_STAGE(PG8_SB(1, 0), b3, voffB); PG8_STAGE(PG8_SB(1, 1), b3 + hstep, voffB); PG8_STAGE(PG8_SA(1, 0), a3, voffA);
;             PG8_WAIT_V(8); PG8_WAIT_L(0); PG8_BAR; PG8_MMA(1, 0, At, B0); PG8_MMA(1, 1, At, B1); PG8_BAR; PG8_SCHED;
	s_setprio 1
	s_waitcnt lgkmcnt(0)
	v_mfma_f32_16x16x32_bf16 v[60:63], v[140:143], v[178:181], v[60:63]
	v_mfma_f32_16x16x32_bf16 v[56:59], v[154:157], v[178:181], v[56:59]
	v_mfma_f32_16x16x32_bf16 v[48:51], v[140:143], v[186:189], v[48:51]
	v_mfma_f32_16x16x32_bf16 v[40:43], v[154:157], v[186:189], v[40:43]
	v_mfma_f32_16x16x32_bf16 v[32:35], v[140:143], v[194:197], v[32:35]
	v_mfma_f32_16x16x32_bf16 v[24:27], v[154:157], v[194:197], v[24:27]
	v_mfma_f32_16x16x32_bf16 v[16:19], v[140:143], v[202:205], v[16:19]
	v_mfma_f32_16x16x32_bf16 v[8:11], v[154:157], v[202:205], v[8:11]
	v_mfma_f32_16x16x32_bf16 v[60:63], v[150:153], v[182:185], v[60:63]
	v_mfma_f32_16x16x32_bf16 v[56:59], v[158:161], v[182:185], v[56:59]
	v_mfma_f32_16x16x32_bf16 v[48:51], v[150:153], v[190:193], v[48:51]
	v_mfma_f32_16x16x32_bf16 v[40:43], v[158:161], v[190:193], v[40:43]
	v_mfma_f32_16x16x32_bf16 v[32:35], v[150:153], v[198:201], v[32:35]
	v_mfma_f32_16x16x32_bf16 v[24:27], v[158:161], v[198:201], v[24:27]
	v_mfma_f32_16x16x32_bf16 v[16:19], v[150:153], v[206:209], v[16:19]
	v_mfma_f32_16x16x32_bf16 v[8:11], v[158:161], v[206:209], v[8:11]
	s_setprio 0
	s_setprio 1
	v_mfma_f32_16x16x32_bf16 v[52:55], v[162:165], v[178:181], v[52:55]
	v_mfma_f32_16x16x32_bf16 v[44:47], v[170:173], v[178:181], v[44:47]
	v_mfma_f32_16x16x32_bf16 v[36:39], v[162:165], v[186:189], v[36:39]
	v_mfma_f32_16x16x32_bf16 v[28:31], v[170:173], v[186:189], v[28:31]
	v_mfma_f32_16x16x32_bf16 v[20:23], v[162:165], v[194:197], v[20:23]
	v_mfma_f32_16x16x32_bf16 v[12:15], v[170:173], v[194:197], v[12:15]
	v_mfma_f32_16x16x32_bf16 v[4:7], v[162:165], v[202:205], v[4:7]
	v_mfma_f32_16x16x32_bf16 v[0:3], v[170:173], v[202:205], v[0:3]
	v_mfma_f32_16x16x32_bf16 v[52:55], v[166:169], v[182:185], v[52:55]
	v_mfma_f32_16x16x32_bf16 v[44:47], v[174:177], v[182:185], v[44:47]
	v_mfma_f32_16x16x32_bf16 v[36:39], v[166:169], v[190:193], v[36:39]
	v_mfma_f32_16x16x32_bf16 v[28:31], v[174:177], v[190:193], v[28:31]
	s_barrier
	s_setprio 3
	v_mfma_f32_16x16x32_bf16 v[20:23], v[166:169], v[198:201], v[20:23]
	v_mfma_f32_16x16x32_bf16 v[12:15], v[174:177], v[198:201], v[12:15]
	v_mfma_f32_16x16x32_bf16 v[4:7], v[166:169], v[206:209], v[4:7]
	v_mfma_f32_16x16x32_bf16 v[0:3], v[174:177], v[206:209], v[0:3]
	s_setprio 0
	s_add_i32 s46, 0, 0x18000
	s_add_i32 s47, 0, 0x1c000
	v_add_u32_e32 v158, s46, v145
	v_add_u32_e32 v174, s47, v145
	ds_read_b128 v[140:143], v158
	ds_read_b128 v[150:153], v158 offset:1024
	ds_read_b128 v[154:157], v158 offset:2048
	ds_read_b128 v[158:161], v158 offset:3072
	ds_read_b128 v[162:165], v174
	ds_read_b128 v[166:169], v174 offset:1024
	ds_read_b128 v[170:173], v174 offset:2048
	ds_read_b128 v[174:177], v174 offset:3072
	s_add_u32 s16, s22, 0x160000
	s_addc_u32 s17, s23, 0
	s_mov_b32 m0, s30
	v_lshl_add_u64 v[218:219], s[16:17], 0, v[128:129]
	ds_read_b128 v[178:181], v149 offset:32768
	ds_read_b128 v[182:185], v149 offset:33792
	ds_read_b128 v[186:189], v149 offset:34816
	ds_read_b128 v[190:193], v149 offset:35840
	ds_read_b128 v[194:197], v149 offset:36864
	ds_read_b128 v[198:201], v149 offset:37888
	ds_read_b128 v[202:205], v149 offset:38912
	ds_read_b128 v[206:209], v149 offset:39936
	global_load_lds_dwordx4 v[218:219], off
	v_lshl_add_u64 v[218:219], s[16:17], 0, v[130:131]
	s_mov_b32 m0, s31
	s_nop 0
	global_load_lds_dwordx4 v[218:219], off
	s_waitcnt vmcnt(8)
	s_waitcnt lgkmcnt(0)
	s_barrier
	s_setprio 1
	s_waitcnt lgkmcnt(0)
	v_mfma_f32_16x16x32_bf16 v[124:127], v[140:143], v[178:181], v[124:127]
	v_mfma_f32_16x16x32_bf16 v[120:123], v[154:157], v[178:181], v[120:123]
	v_mfma_f32_16x16x32_bf16 v[112:115], v[140:143], v[186:189], v[112:115]
	v_mfma_f32_16x16x32_bf16 v[104:107], v[154:157], v[186:189], v[104:107]
	v_mfma_f32_16x16x32_bf16 v[96:99], v[140:143], v[194:197], v[96:99]
	v_mfma_f32_16x16x32_bf16 v[88:91], v[154:157], v[194:197], v[88:91]
	v_mfma_f32_16x16x32_bf16 v[80:83], v[140:143], v[202:205], v[80:83]
	v_mfma_f32_16x16x32_bf16 v[72:75], v[154:157], v[202:205], v[72:75]
	v_mfma_f32_16x16x32_bf16 v[124:127], v[150:153], v[182:185], v[124:127]
	v_mfma_f32_16x16x32_bf16 v[120:123], v[158:161], v[182:185], v[120:123]
	v_mfma_f32_16x16x32_bf16 v[112:115], v[150:153], v[190:193], v[112:115]
	v_mfma_f32_16x16x32_bf16 v[104:107], v[158:161], v[190:193], v[104:107]
	v_mfma_f32_16x16x32_bf16 v[96:99], v[150:153], v[198:201], v[96:99]
	v_mfma_f32_16x16x32_bf16 v[88:91], v[158:161], v[198:201], v[88:91]
	v_mfma_f32_16x16x32_bf16 v[80:83], v[150:153], v[206:209], v[80:83]
	v_mfma_f32_16x16x32_bf16 v[72:75], v[158:161], v[206:209], v[72:75]
	s_setprio 0
	s_setprio 1
	v_mfma_f32_16x16x32_bf16 v[116:119], v[162:165], v[178:181], v[116:119]
	v_mfma_f32_16x16x32_bf16 v[108:111], v[170:173], v[178:181], v[108:111]
	v_mfma_f32_16x16x32_bf16 v[100:103], v[162:165], v[186:189], v[100:103]
	v_mfma_f32_16x16x32_bf16 v[92:95], v[170:173], v[186:189], v[92:95]
	v_mfma_f32_16x16x32_bf16 v[84:87], v[162:165], v[194:197], v[84:87]
	v_mfma_f32_16x16x32_bf16 v[76:79], v[170:173], v[194:197], v[76:79]
	v_mfma_f32_16x16x32_bf16 v[68:71], v[162:165], v[202:205], v[68:71]
	v_mfma_f32_16x16x32_bf16 v[64:67], v[170:173], v[202:205], v[64:67]
	v_mfma_f32_16x16x32_bf16 v[116:119], v[166:169], v[182:185], v[116:119]
	v_mfma_f32_16x16x32_bf16 v[108:111], v[174:177], v[182:185], v[108:111]
	v_mfma_f32_16x16x32_bf16 v[100:103], v[166:169], v[190:193], v[100:103]
	v_mfma_f32_16x16x32_bf16 v[92:95], v[174:177], v[190:193], v[92:95]
	s_barrier
; #define PG8_STAGE(bufoff, gbase, voff) do { _Pragma("unroll") for (int _i = 0; _i < 2; ++_i) \
;         __builtin_amdgcn_global_load_lds((const unsigned*)((const char*)(gbase) + (voff)[_i]), (PG8_LAS unsigned*)(lds + (bufoff) + ldsw + _i * 8192), 16, 0, 0); } while (0)
; #define PG8_LDA(dst, b, h) do { _Pragma("unroll") for (int m = 0; m < 4; ++m) _Pragma("unroll") for (int k = 0; k < 2; ++k) dst[m][k] = *(const PG8_LAS bf16x8*)(lds + PG8_SA(b, h) + aoff + m * 2048 + k * 1024); } while (0)
; #define PG8_MMA(ai, bj, At, Bt) do { __builtin_amdgcn_s_setprio(1); _Pragma("unroll") for (int m = 0; m < 4; ++m) _Pragma("unroll") for (int n = 0; n < 2; ++n) _Pragma("unroll") for (int k = 0; k < 2; ++k) \
;         acc[ai][bj][m][n] = __builtin_amdgcn_mfma_f32_16x16x32_bf16(Bt[n][k], At[m][k], acc[ai][bj][m][n], 0, 0, 0); __builtin_amdgcn_s_setprio(0); } while (0)
; #define PG8_WAIT_V(n) asm volatile("s_waitcnt vmcnt(" #n ")" ::: "memory")
; #define PG8_WAIT_L(n) asm volatile("s_waitcnt lgkmcnt(" #n ")" ::: "memory")
; #define PG8_BAR __builtin_amdgcn_s_barrier()
; #define PG8_SCHED __builtin_amdgcn_sched_barrier(0)
;     __device__ __forceinline__ void operator()(const f32x4 (&acc)[2][2][4][2], const Unit& u, int wr, int wc, int fr, int fq) const {
;     ...
;             for (int m = 0; m < 4; ++m) { const size_t off = (size_t)(u.pm * BM + ai * HALF + wr * 64 + m * 16 + fr) * ldc + col0;
; #pragma unroll
;                 for (int bj = 0; bj < 2; ++bj)
; #pragma unroll
;                     for (int n = 0; n < 2; ++n) { const u32x2 t = *(const u32x2*)(base + off + bj * HALF + n * 16);
; template <class Epi, class Sched, bool ALIGN_EPI = false, bool SP2 = false>
; __device__ __forceinline__ void gemm_phase(PG8_LAS unsigned char* lds, const Gemm g, const Sched& S, const Epi& E, int wave_in) {
;     ...
;             PG8_WAIT_V(8); PG8_WAIT_L(0); PG8_BAR; PG8_MMA(0, 0, At, B0); PG8_MMA(0, 1, At, B1); PG8_BAR; PG8_SCHED;
;             PG8_LDA(At, 1, 1); PG8_STAGE(PG8_SB(1, 0), b3, voffB); PG8_STAGE(PG8_SB(1, 1), b3 + hstep, voffB); PG8_STAGE(PG8_SA(1, 0), a3, voffA);
;             PG8_WAIT_V(8); PG8_WAIT_L(0); PG8_BAR; PG8_MMA(1, 0, At, B0); PG8_MMA(1, 1, At, B1); PG8_BAR; PG8_SCHED;
	s_setprio 3
	v_mfma_f32_16x16x32_bf16 v[84:87], v[166:169], v[198:201], v[84:87]
	v_mfma_f32_16x16x32_bf16 v[76:79], v[174:177], v[198:201], v[76:79]
	v_mfma_f32_16x16x32_bf16 v[68:71], v[166:169], v[206:209], v[68:71]
	v_mfma_f32_16x16x32_bf16 v[64:67], v[174:177], v[206:209], v[64:67]
	s_setprio 0
	s_add_i32 s16, s46, s25
	v_lshl_add_u64 v[210:211], v[210:211], 0, s[6:7]
	s_mov_b32 m0, s16
	ds_read_b128 v[178:181], v149 offset:49152
	ds_read_b128 v[182:185], v149 offset:50176
	ds_read_b128 v[186:189], v149 offset:51200
	ds_read_b128 v[190:193], v149 offset:52224
	ds_read_b128 v[194:197], v149 offset:53248
	ds_read_b128 v[198:201], v149 offset:54272
	ds_read_b128 v[202:205], v149 offset:55296
	ds_read_b128 v[206:209], v149 offset:56320
	global_load_lds_dwordx4 v[210:211], off
	s_add_i32 m0, s16, 0x2000
	s_add_u32 s16, s20, 0x160080
	v_lshl_add_u64 v[210:211], v[212:213], 0, s[6:7]
	s_addc_u32 s17, s21, 0
	s_add_i32 s20, s47, s25
	global_load_lds_dwordx4 v[210:211], off
	v_lshl_add_u64 v[210:211], s[16:17], 0, v[128:129]
	s_mov_b32 m0, s20
	s_nop 0
	global_load_lds_dwordx4 v[210:211], off
	v_lshl_add_u64 v[210:211], s[16:17], 0, v[130:131]
	s_add_i32 m0, s20, 0x2000
	s_nop 0
	global_load_lds_dwordx4 v[210:211], off
	v_lshl_add_u64 v[210:211], v[214:215], 0, s[6:7]
	s_mov_b32 m0, s34
	s_nop 0
	global_load_lds_dwordx4 v[210:211], off
	v_lshl_add_u64 v[210:211], v[216:217], 0, s[6:7]
	s_mov_b32 m0, s35
	s_nop 0
	global_load_lds_dwordx4 v[210:211], off
	s_waitcnt vmcnt(8)
	s_waitcnt lgkmcnt(0)
	s_barrier
	s_setprio 1
	s_waitcnt lgkmcnt(0)
	v_mfma_f32_16x16x32_bf16 v[60:63], v[140:143], v[178:181], v[60:63]
	v_mfma_f32_16x16x32_bf16 v[56:59], v[154:157], v[178:181], v[56:59]
	v_mfma_f32_16x16x32_bf16 v[48:51], v[140:143], v[186:189], v[48:51]
	v_mfma_f32_16x16x32_bf16 v[40:43], v[154:157], v[186:189], v[40:43]
	v_mfma_f32_16x16x32_bf16 v[32:35], v[140:143], v[194:197], v[32:35]
	v_mfma_f32_16x16x32_bf16 v[24:27], v[154:157], v[194:197], v[24:27]
	v_mfma_f32_16x16x32_bf16 v[16:19], v[140:143], v[202:205], v[16:19]
	v_mfma_f32_16x16x32_bf16 v[8:11], v[154:157], v[202:205], v[8:11]
	v_mfma_f32_16x16x32_bf16 v[60:63], v[150:153], v[182:185], v[60:63]
	v_mfma_f32_16x16x32_bf16 v[56:59], v[158:161], v[182:185], v[56:59]
	v_mfma_f32_16x16x32_bf16 v[48:51], v[150:153], v[190:193], v[48:51]
	v_mfma_f32_16x16x32_bf16 v[40:43], v[158:161], v[190:193], v[40:43]
	v_mfma_f32_16x16x32_bf16 v[32:35], v[150:153], v[198:201], v[32:35]
	v_mfma_f32_16x16x32_bf16 v[24:27], v[158:161], v[198:201], v[24:27]
	v_mfma_f32_16x16x32_bf16 v[16:19], v[150:153], v[206:209], v[16:19]
	v_mfma_f32_16x16x32_bf16 v[8:11], v[158:161], v[206:209], v[8:11]
	s_setprio 0
	s_setprio 1
	v_mfma_f32_16x16x32_bf16 v[52:55], v[162:165], v[178:181], v[52:55]
	v_mfma_f32_16x16x32_bf16 v[44:47], v[170:173], v[178:181], v[44:47]
	v_mfma_f32_16x16x32_bf16 v[36:39], v[162:165], v[186:189], v[36:39]
	v_mfma_f32_16x16x32_bf16 v[28:31], v[170:173], v[186:189], v[28:31]
	v_mfma_f32_16x16x32_bf16 v[20:23], v[162:165], v[194:197], v[20:23]
	v_mfma_f32_16x16x32_bf16 v[12:15], v[170:173], v[194:197], v[12:15]
	v_mfma_f32_16x16x32_bf16 v[4:7], v[162:165], v[202:205], v[4:7]
	v_mfma_f32_16x16x32_bf16 v[0:3], v[170:173], v[202:205], v[0:3]
	v_mfma_f32_16x16x32_bf16 v[52:55], v[166:169], v[182:185], v[52:55]
	v_mfma_f32_16x16x32_bf16 v[44:47], v[174:177], v[182:185], v[44:47]
	v_mfma_f32_16x16x32_bf16 v[36:39], v[166:169], v[190:193], v[36:39]
	v_mfma_f32_16x16x32_bf16 v[28:31], v[174:177], v[190:193], v[28:31]
	s_barrier
	s_setprio 3
	v_mfma_f32_16x16x32_bf16 v[20:23], v[166:169], v[198:201], v[20:23]
	v_mfma_f32_16x16x32_bf16 v[12:15], v[174:177], v[198:201], v[12:15]
	v_mfma_f32_16x16x32_bf16 v[4:7], v[166:169], v[206:209], v[4:7]
	v_mfma_f32_16x16x32_bf16 v[0:3], v[174:177], v[206:209], v[0:3]
	s_setprio 0
	s_add_i32 s45, s45, 2
	s_add_u32 s43, s43, 0x100
	s_addc_u32 s44, s44, 0
	s_cmpk_gt_u32 s45, 0x55
	s_mov_b64 s[16:17], s[18:19]
	s_cbranch_scc0 .LBB0_1009
	v_lshl_add_u32 v142, s41, 8, v144
	v_lshl_or_b32 v140, s42, 8, v146
	v_lshlrev_b32_e32 v143, 12, v142
	v_lshl_add_u32 v143, v140, 1, v143
	v_mov_b32_e32 v140, v143
	global_load_dwordx2 v[152:153], v140, s[10:11]
	global_load_dwordx2 v[154:155], v140, s[10:11] offset:32
	global_load_dwordx2 v[156:157], v140, s[10:11] offset:256
	global_load_dwordx2 v[158:159], v140, s[10:11] offset:288
	v_add_u32_e32 v140, 0x10000, v143
	global_load_dwordx2 v[160:161], v140, s[10:11]
	global_load_dwordx2 v[162:163], v140, s[10:11] offset:32
	global_load_dwordx2 v[164:165], v140, s[10:11] offset:256
	global_load_dwordx2 v[166:167], v140, s[10:11] offset:288
	v_add_u32_e32 v140, 0x20000, v143
	global_load_dwordx2 v[168:169], v140, s[10:11]
	global_load_dwordx2 v[170:171], v140, s[10:11] offset:32
	global_load_dwordx2 v[172:173], v140, s[10:11] offset:256
	global_load_dwordx2 v[174:175], v140, s[10:11] offset:288
	v_add_u32_e32 v140, 0x30000, v143
	global_load_dwordx2 v[176:177], v140, s[10:11]
	global_load_dwordx2 v[178:179], v140, s[10:11] offset:32
	global_load_dwordx2 v[180:181], v140, s[10:11] offset:256
	global_load_dwordx2 v[182:183], v140, s[10:11] offset:288
	v_add_u32_e32 v140, 0x80000, v143
	global_load_dwordx2 v[184:185], v140, s[10:11]
	global_load_dwordx2 v[186:187], v140, s[10:11] offset:32
	global_load_dwordx2 v[188:189], v140, s[10:11] offset:256
	global_load_dwordx2 v[190:191], v140, s[10:11] offset:288
	v_add_u32_e32 v140, 0x90000, v143
	global_load_dwordx2 v[192:193], v140, s[10:11]
	global_load_dwordx2 v[194:195], v140, s[10:11] offset:32
	global_load_dwordx2 v[196:197], v140, s[10:11] offset:256
	global_load_dwordx2 v[198:199], v140, s[10:11] offset:288
	v_add_u32_e32 v140, 0xa0000, v143
	global_load_dwordx2 v[200:201], v140, s[10:11]
	global_load_dwordx2 v[202:203], v140, s[10:11] offset:32
	global_load_dwordx2 v[204:205], v140, s[10:11] offset:256
	global_load_dwordx2 v[206:207], v140, s[10:11] offset:288
	v_add_u32_e32 v140, 0xb0000, v143
	global_load_dwordx2 v[208:209], v140, s[10:11]
	global_load_dwordx2 v[210:211], v140, s[10:11] offset:32
	global_load_dwordx2 v[212:213], v140, s[10:11] offset:256
	global_load_dwordx2 v[214:215], v140, s[10:11] offset:288
	s_and_b64 vcc, exec, s[12:13]
	s_cbranch_vccz .LBB0_1012
	s_barrier
;     __device__ __forceinline__ void operator()(const f32x4 (&acc)[2][2][4][2], const Unit& u, int wr, int wc, int fr, int fq) const {
;     ...
;         for (int ai = 0; ai < 2; ++ai)
; #pragma unroll
;             for (int m = 0; m < 4; ++m) { const size_t off = (size_t)(u.pm * BM + ai * HALF + wr * 64 + m * 16 + fr) * ldc + col0;
; #pragma unroll
;                 for (int bj = 0; bj < 2; ++bj)
; #pragma unroll
;                     for (int n = 0; n < 2; ++n) { const u32x2 t = *(const u32x2*)(base + off + bj * HALF + n * 16);
;                         const f32x4 bs = (f32x4){__builtin_bit_cast(float, t.x << 16), __builtin_bit_cast(float, t.x & 0xffff0000u), __builtin_bit_cast(float, t.y << 16), __builtin_bit_cast(float, t.y & 0xffff0000u)};
;                         *(f32x4*)(out + off + bj * HALF + n * 16) = bs + acc[ai][bj][m][n] * scale; } }
.LBB0_1012:
	s_and_b64 vcc, exec, s[0:1]
	s_mov_b64 s[0:1], -1
	v_lshlrev_b32_e32 v142, 1, v143
	s_waitcnt vmcnt(28)
	v_mov_b32_e32 v140, v142
	v_lshlrev_b32_e32 v216, 16, v152
	v_and_b32_e32 v217, 0xffff0000, v152
	v_lshlrev_b32_e32 v218, 16, v153
	v_and_b32_e32 v219, 0xffff0000, v153
	v_pk_fma_f32 v[124:125], v[124:125], 0.5, v[216:217] op_sel_hi:[1,0,1]
	v_pk_fma_f32 v[126:127], v[126:127], 0.5, v[218:219] op_sel_hi:[1,0,1]
	global_store_dwordx4 v140, v[124:127], s[8:9]
	v_lshlrev_b32_e32 v216, 16, v154
	v_and_b32_e32 v217, 0xffff0000, v154
	v_lshlrev_b32_e32 v218, 16, v155
	v_and_b32_e32 v219, 0xffff0000, v155
	v_pk_fma_f32 v[120:121], v[120:121], 0.5, v[216:217] op_sel_hi:[1,0,1]
	v_pk_fma_f32 v[122:123], v[122:123], 0.5, v[218:219] op_sel_hi:[1,0,1]
	global_store_dwordx4 v140, v[120:123], s[8:9] offset:64
	v_lshlrev_b32_e32 v216, 16, v156
	v_and_b32_e32 v217, 0xffff0000, v156
	v_lshlrev_b32_e32 v218, 16, v157
	v_and_b32_e32 v219, 0xffff0000, v157
	v_pk_fma_f32 v[116:117], v[116:117], 0.5, v[216:217] op_sel_hi:[1,0,1]
	v_pk_fma_f32 v[118:119], v[118:119], 0.5, v[218:219] op_sel_hi:[1,0,1]
	global_store_dwordx4 v140, v[116:119], s[8:9] offset:512
	v_lshlrev_b32_e32 v216, 16, v158
	v_and_b32_e32 v217, 0xffff0000, v158
	v_lshlrev_b32_e32 v218, 16, v159
	v_and_b32_e32 v219, 0xffff0000, v159
	v_pk_fma_f32 v[108:109], v[108:109], 0.5, v[216:217] op_sel_hi:[1,0,1]
	v_pk_fma_f32 v[110:111], v[110:111], 0.5, v[218:219] op_sel_hi:[1,0,1]
	global_store_dwordx4 v140, v[108:111], s[8:9] offset:576
	s_waitcnt vmcnt(28)
	v_add_u32_e32 v140, 0x20000, v142
	v_lshlrev_b32_e32 v216, 16, v160
	v_and_b32_e32 v217, 0xffff0000, v160
	v_lshlrev_b32_e32 v218, 16, v161
	v_and_b32_e32 v219, 0xffff0000, v161
	v_pk_fma_f32 v[112:113], v[112:113], 0.5, v[216:217] op_sel_hi:[1,0,1]
	v_pk_fma_f32 v[114:115], v[114:115], 0.5, v[218:219] op_sel_hi:[1,0,1]
	global_store_dwordx4 v140, v[112:115], s[8:9]
	v_lshlrev_b32_e32 v216, 16, v162
	v_and_b32_e32 v217, 0xffff0000, v162
	v_lshlrev_b32_e32 v218, 16, v163
	v_and_b32_e32 v219, 0xffff0000, v163
	v_pk_fma_f32 v[104:105], v[104:105], 0.5, v[216:217] op_sel_hi:[1,0,1]
	v_pk_fma_f32 v[106:107], v[106:107], 0.5, v[218:219] op_sel_hi:[1,0,1]
	global_store_dwordx4 v140, v[104:107], s[8:9] offset:64
	v_lshlrev_b32_e32 v216, 16, v164
	v_and_b32_e32 v217, 0xffff0000, v164
	v_lshlrev_b32_e32 v218, 16, v165
	v_and_b32_e32 v219, 0xffff0000, v165
	v_pk_fma_f32 v[100:101], v[100:101], 0.5, v[216:217] op_sel_hi:[1,0,1]
	v_pk_fma_f32 v[102:103], v[102:103], 0.5, v[218:219] op_sel_hi:[1,0,1]
	global_store_dwordx4 v140, v[100:103], s[8:9] offset:512
	v_lshlrev_b32_e32 v216, 16, v166
	v_and_b32_e32 v217, 0xffff0000, v166
	v_lshlrev_b32_e32 v218, 16, v167
	v_and_b32_e32 v219, 0xffff0000, v167
	v_pk_fma_f32 v[92:93], v[92:93], 0.5, v[216:217] op_sel_hi:[1,0,1]
	v_pk_fma_f32 v[94:95], v[94:95], 0.5, v[218:219] op_sel_hi:[1,0,1]
	global_store_dwordx4 v140, v[92:95], s[8:9] offset:576
	s_waitcnt vmcnt(28)
	v_add_u32_e32 v140, 0x40000, v142
	v_lshlrev_b32_e32 v216, 16, v168
	v_and_b32_e32 v217, 0xffff0000, v168
	v_lshlrev_b32_e32 v218, 16, v169
	v_and_b32_e32 v219, 0xffff0000, v169
	v_pk_fma_f32 v[96:97], v[96:97], 0.5, v[216:217] op_sel_hi:[1,0,1]
	v_pk_fma_f32 v[98:99], v[98:99], 0.5, v[218:219] op_sel_hi:[1,0,1]
	global_store_dwordx4 v140, v[96:99], s[8:9]
	v_lshlrev_b32_e32 v216, 16, v170
	v_and_b32_e32 v217, 0xffff0000, v170
	v_lshlrev_b32_e32 v218, 16, v171
	v_and_b32_e32 v219, 0xffff0000, v171
	v_pk_fma_f32 v[88:89], v[88:89], 0.5, v[216:217] op_sel_hi:[1,0,1]
	v_pk_fma_f32 v[90:91], v[90:91], 0.5, v[218:219] op_sel_hi:[1,0,1]
	global_store_dwordx4 v140, v[88:91], s[8:9] offset:64
	v_lshlrev_b32_e32 v216, 16, v172
	v_and_b32_e32 v217, 0xffff0000, v172
	v_lshlrev_b32_e32 v218, 16, v173
	v_and_b32_e32 v219, 0xffff0000, v173
	v_pk_fma_f32 v[84:85], v[84:85], 0.5, v[216:217] op_sel_hi:[1,0,1]
	v_pk_fma_f32 v[86:87], v[86:87], 0.5, v[218:219] op_sel_hi:[1,0,1]
	global_store_dwordx4 v140, v[84:87], s[8:9] offset:512
	v_lshlrev_b32_e32 v216, 16, v174
	v_and_b32_e32 v217, 0xffff0000, v174
	v_lshlrev_b32_e32 v218, 16, v175
	v_and_b32_e32 v219, 0xffff0000, v175
	v_pk_fma_f32 v[76:77], v[76:77], 0.5, v[216:217] op_sel_hi:[1,0,1]
	v_pk_fma_f32 v[78:79], v[78:79], 0.5, v[218:219] op_sel_hi:[1,0,1]
	global_store_dwordx4 v140, v[76:79], s[8:9] offset:576
	s_waitcnt vmcnt(28)
	v_add_u32_e32 v140, 0x60000, v142
	v_lshlrev_b32_e32 v216, 16, v176
	v_and_b32_e32 v217, 0xffff0000, v176
	v_lshlrev_b32_e32 v218, 16, v177
	v_and_b32_e32 v219, 0xffff0000, v177
	v_pk_fma_f32 v[80:81], v[80:81], 0.5, v[216:217] op_sel_hi:[1,0,1]
	v_pk_fma_f32 v[82:83], v[82:83], 0.5, v[218:219] op_sel_hi:[1,0,1]
	global_store_dwordx4 v140, v[80:83], s[8:9]
	v_lshlrev_b32_e32 v216, 16, v178
	v_and_b32_e32 v217, 0xffff0000, v178
	v_lshlrev_b32_e32 v218, 16, v179
	v_and_b32_e32 v219, 0xffff0000, v179
	v_pk_fma_f32 v[72:73], v[72:73], 0.5, v[216:217] op_sel_hi:[1,0,1]
	v_pk_fma_f32 v[74:75], v[74:75], 0.5, v[218:219] op_sel_hi:[1,0,1]
	global_store_dwordx4 v140, v[72:75], s[8:9] offset:64
	v_lshlrev_b32_e32 v216, 16, v180
	v_and_b32_e32 v217, 0xffff0000, v180
	v_lshlrev_b32_e32 v218, 16, v181
	v_and_b32_e32 v219, 0xffff0000, v181
	v_pk_fma_f32 v[68:69], v[68:69], 0.5, v[216:217] op_sel_hi:[1,0,1]
	v_pk_fma_f32 v[70:71], v[70:71], 0.5, v[218:219] op_sel_hi:[1,0,1]
	global_store_dwordx4 v140, v[68:71], s[8:9] offset:512
	v_lshlrev_b32_e32 v216, 16, v182
	v_and_b32_e32 v217, 0xffff0000, v182
	v_lshlrev_b32_e32 v218, 16, v183
	v_and_b32_e32 v219, 0xffff0000, v183
	v_pk_fma_f32 v[64:65], v[64:65], 0.5, v[216:217] op_sel_hi:[1,0,1]
	v_pk_fma_f32 v[66:67], v[66:67], 0.5, v[218:219] op_sel_hi:[1,0,1]
	global_store_dwordx4 v140, v[64:67], s[8:9] offset:576
	s_waitcnt vmcnt(28)
;     __device__ __forceinline__ void operator()(const f32x4 (&acc)[2][2][4][2], const Unit& u, int wr, int wc, int fr, int fq) const {
;     ...
;         for (int ai = 0; ai < 2; ++ai)
; #pragma unroll
;             for (int m = 0; m < 4; ++m) { const size_t off = (size_t)(u.pm * BM + ai * HALF + wr * 64 + m * 16 + fr) * ldc + col0;
; #pragma unroll
;                 for (int bj = 0; bj < 2; ++bj)
; #pragma unroll
;                     for (int n = 0; n < 2; ++n) { const u32x2 t = *(const u32x2*)(base + off + bj * HALF + n * 16);
;                         const f32x4 bs = (f32x4){__builtin_bit_cast(float, t.x << 16), __builtin_bit_cast(float, t.x & 0xffff0000u), __builtin_bit_cast(float, t.y << 16), __builtin_bit_cast(float, t.y & 0xffff0000u)};
;                         *(f32x4*)(out + off + bj * HALF + n * 16) = bs + acc[ai][bj][m][n] * scale; } }
	v_add_u32_e32 v140, 0x100000, v142
	v_lshlrev_b32_e32 v216, 16, v184
	v_and_b32_e32 v217, 0xffff0000, v184
	v_lshlrev_b32_e32 v218, 16, v185
	v_and_b32_e32 v219, 0xffff0000, v185
	v_pk_fma_f32 v[60:61], v[60:61], 0.5, v[216:217] op_sel_hi:[1,0,1]
	v_pk_fma_f32 v[62:63], v[62:63], 0.5, v[218:219] op_sel_hi:[1,0,1]
	global_store_dwordx4 v140, v[60:63], s[8:9]
	v_lshlrev_b32_e32 v216, 16, v186
	v_and_b32_e32 v217, 0xffff0000, v186
	v_lshlrev_b32_e32 v218, 16, v187
	v_and_b32_e32 v219, 0xffff0000, v187
	v_pk_fma_f32 v[56:57], v[56:57], 0.5, v[216:217] op_sel_hi:[1,0,1]
	v_pk_fma_f32 v[58:59], v[58:59], 0.5, v[218:219] op_sel_hi:[1,0,1]
	global_store_dwordx4 v140, v[56:59], s[8:9] offset:64
	v_lshlrev_b32_e32 v216, 16, v188
	v_and_b32_e32 v217, 0xffff0000, v188
	v_lshlrev_b32_e32 v218, 16, v189
	v_and_b32_e32 v219, 0xffff0000, v189
	v_pk_fma_f32 v[52:53], v[52:53], 0.5, v[216:217] op_sel_hi:[1,0,1]
	v_pk_fma_f32 v[54:55], v[54:55], 0.5, v[218:219] op_sel_hi:[1,0,1]
	global_store_dwordx4 v140, v[52:55], s[8:9] offset:512
	v_lshlrev_b32_e32 v216, 16, v190
	v_and_b32_e32 v217, 0xffff0000, v190
	v_lshlrev_b32_e32 v218, 16, v191
	v_and_b32_e32 v219, 0xffff0000, v191
	v_pk_fma_f32 v[44:45], v[44:45], 0.5, v[216:217] op_sel_hi:[1,0,1]
	v_pk_fma_f32 v[46:47], v[46:47], 0.5, v[218:219] op_sel_hi:[1,0,1]
	global_store_dwordx4 v140, v[44:47], s[8:9] offset:576
	s_waitcnt vmcnt(28)
	v_add_u32_e32 v140, 0x120000, v142
	v_lshlrev_b32_e32 v216, 16, v192
	v_and_b32_e32 v217, 0xffff0000, v192
	v_lshlrev_b32_e32 v218, 16, v193
	v_and_b32_e32 v219, 0xffff0000, v193
	v_pk_fma_f32 v[48:49], v[48:49], 0.5, v[216:217] op_sel_hi:[1,0,1]
	v_pk_fma_f32 v[50:51], v[50:51], 0.5, v[218:219] op_sel_hi:[1,0,1]
	global_store_dwordx4 v140, v[48:51], s[8:9]
	v_lshlrev_b32_e32 v216, 16, v194
	v_and_b32_e32 v217, 0xffff0000, v194
	v_lshlrev_b32_e32 v218, 16, v195
	v_and_b32_e32 v219, 0xffff0000, v195
	v_pk_fma_f32 v[40:41], v[40:41], 0.5, v[216:217] op_sel_hi:[1,0,1]
	v_pk_fma_f32 v[42:43], v[42:43], 0.5, v[218:219] op_sel_hi:[1,0,1]
	global_store_dwordx4 v140, v[40:43], s[8:9] offset:64
	v_lshlrev_b32_e32 v216, 16, v196
	v_and_b32_e32 v217, 0xffff0000, v196
	v_lshlrev_b32_e32 v218, 16, v197
	v_and_b32_e32 v219, 0xffff0000, v197
	v_pk_fma_f32 v[36:37], v[36:37], 0.5, v[216:217] op_sel_hi:[1,0,1]
	v_pk_fma_f32 v[38:39], v[38:39], 0.5, v[218:219] op_sel_hi:[1,0,1]
	global_store_dwordx4 v140, v[36:39], s[8:9] offset:512
	v_lshlrev_b32_e32 v216, 16, v198
	v_and_b32_e32 v217, 0xffff0000, v198
	v_lshlrev_b32_e32 v218, 16, v199
	v_and_b32_e32 v219, 0xffff0000, v199
	v_pk_fma_f32 v[28:29], v[28:29], 0.5, v[216:217] op_sel_hi:[1,0,1]
	v_pk_fma_f32 v[30:31], v[30:31], 0.5, v[218:219] op_sel_hi:[1,0,1]
	global_store_dwordx4 v140, v[28:31], s[8:9] offset:576
	s_waitcnt vmcnt(28)
	v_add_u32_e32 v140, 0x140000, v142
	v_lshlrev_b32_e32 v216, 16, v200
	v_and_b32_e32 v217, 0xffff0000, v200
	v_lshlrev_b32_e32 v218, 16, v201
	v_and_b32_e32 v219, 0xffff0000, v201
	v_pk_fma_f32 v[32:33], v[32:33], 0.5, v[216:217] op_sel_hi:[1,0,1]
	v_pk_fma_f32 v[34:35], v[34:35], 0.5, v[218:219] op_sel_hi:[1,0,1]
	global_store_dwordx4 v140, v[32:35], s[8:9]
	v_lshlrev_b32_e32 v216, 16, v202
	v_and_b32_e32 v217, 0xffff0000, v202
	v_lshlrev_b32_e32 v218, 16, v203
	v_and_b32_e32 v219, 0xffff0000, v203
	v_pk_fma_f32 v[24:25], v[24:25], 0.5, v[216:217] op_sel_hi:[1,0,1]
	v_pk_fma_f32 v[26:27], v[26:27], 0.5, v[218:219] op_sel_hi:[1,0,1]
	global_store_dwordx4 v140, v[24:27], s[8:9] offset:64
	v_lshlrev_b32_e32 v216, 16, v204
	v_and_b32_e32 v217, 0xffff0000, v204
	v_lshlrev_b32_e32 v218, 16, v205
	v_and_b32_e32 v219, 0xffff0000, v205
	v_pk_fma_f32 v[20:21], v[20:21], 0.5, v[216:217] op_sel_hi:[1,0,1]
	v_pk_fma_f32 v[22:23], v[22:23], 0.5, v[218:219] op_sel_hi:[1,0,1]
	global_store_dwordx4 v140, v[20:23], s[8:9] offset:512
	v_lshlrev_b32_e32 v216, 16, v206
	v_and_b32_e32 v217, 0xffff0000, v206
	v_lshlrev_b32_e32 v218, 16, v207
	v_and_b32_e32 v219, 0xffff0000, v207
	v_pk_fma_f32 v[12:13], v[12:13], 0.5, v[216:217] op_sel_hi:[1,0,1]
	v_pk_fma_f32 v[14:15], v[14:15], 0.5, v[218:219] op_sel_hi:[1,0,1]
	global_store_dwordx4 v140, v[12:15], s[8:9] offset:576
	s_waitcnt vmcnt(28)
	v_add_u32_e32 v140, 0x160000, v142
	v_lshlrev_b32_e32 v216, 16, v208
	v_and_b32_e32 v217, 0xffff0000, v208
	v_lshlrev_b32_e32 v218, 16, v209
	v_and_b32_e32 v219, 0xffff0000, v209
	v_pk_fma_f32 v[16:17], v[16:17], 0.5, v[216:217] op_sel_hi:[1,0,1]
	v_pk_fma_f32 v[18:19], v[18:19], 0.5, v[218:219] op_sel_hi:[1,0,1]
	global_store_dwordx4 v140, v[16:19], s[8:9]
	v_lshlrev_b32_e32 v216, 16, v210
	v_and_b32_e32 v217, 0xffff0000, v210
	v_lshlrev_b32_e32 v218, 16, v211
	v_and_b32_e32 v219, 0xffff0000, v211
	v_pk_fma_f32 v[8:9], v[8:9], 0.5, v[216:217] op_sel_hi:[1,0,1]
	v_pk_fma_f32 v[10:11], v[10:11], 0.5, v[218:219] op_sel_hi:[1,0,1]
	global_store_dwordx4 v140, v[8:11], s[8:9] offset:64
	v_lshlrev_b32_e32 v216, 16, v212
	v_and_b32_e32 v217, 0xffff0000, v212
	v_lshlrev_b32_e32 v218, 16, v213
	v_and_b32_e32 v219, 0xffff0000, v213
	v_pk_fma_f32 v[4:5], v[4:5], 0.5, v[216:217] op_sel_hi:[1,0,1]
	v_pk_fma_f32 v[6:7], v[6:7], 0.5, v[218:219] op_sel_hi:[1,0,1]
	global_store_dwordx4 v140, v[4:7], s[8:9] offset:512
	v_lshlrev_b32_e32 v216, 16, v214
	v_and_b32_e32 v217, 0xffff0000, v214
	v_lshlrev_b32_e32 v218, 16, v215
	v_and_b32_e32 v219, 0xffff0000, v215
	v_pk_fma_f32 v[0:1], v[0:1], 0.5, v[216:217] op_sel_hi:[1,0,1]
	v_pk_fma_f32 v[2:3], v[2:3], 0.5, v[218:219] op_sel_hi:[1,0,1]
	global_store_dwordx4 v140, v[0:3], s[8:9] offset:576
	s_cbranch_vccnz .LBB0_997
	s_andn2_b64 vcc, exec, s[2:3]
	s_cbranch_vccnz .LBB0_996
	s_barrier
	s_branch .LBB0_996
